# nt hint on the out-projection residual-stream (XB) row stores only
# speedup vs baseline: 1.0153x; 1.0015x over previous
.Lfo_entry:
	s_and_b64 vcc, exec, s[28:29]
	s_cbranch_vccz .Lfo_first
	s_lshr_b32 s14, s34, 3
	s_mul_i32 s14, s14, 0x3000
	s_add_u32 s16, s86, s14
	s_addc_u32 s17, s87, 0
	s_add_u32 s16, s16, 0x2000
	s_addc_u32 s17, s17, 0
	s_add_u32 s86, s88, s14
	s_addc_u32 s87, s89, 0
	s_add_u32 s86, s86, 0x1000
	s_addc_u32 s87, s87, 0
	v_lshl_add_u32 v171, v170, 1, v96
	v_lshl_add_u32 v171, v222, 11, v171
	v_lshlrev_b32_e32 v170, 2, v170
	s_lshl_b32 s14, s34, 8
	s_add_i32 s14, s14, s81
	s_lshl_b32 s12, s14, 11
	s_add_u32 s14, s2, s12
	s_addc_u32 s15, s3, 0
	s_add_u32 s78, s78, s12
	s_addc_u32 s79, s79, 0
	s_add_u32 s22, s78, 0x4000
	s_addc_u32 s23, s79, 0
	s_mov_b64 s[2:3], s[14:15]
	s_add_u32 s18, s14, 0x4000
	s_addc_u32 s19, s15, 0
	s_mov_b64 s[12:13], s[18:19]
	s_and_b64 vcc, exec, s[40:41]
	s_cbranch_vccz .Lfo_nong
	global_load_dwordx4 v[142:145], v170, s[16:17]
	global_load_dwordx4 v[150:153], v170, s[16:17] offset:16
	global_load_dwordx4 v[138:141], v170, s[16:17] offset:128
	global_load_dwordx4 v[146:149], v170, s[16:17] offset:144
	global_load_dwordx4 v[196:199], v171, s[14:15]
	global_load_dwordx4 v[200:203], v171, s[12:13]
	s_add_u32 s14, s14, 0x8000
	s_addc_u32 s15, s15, 0
	s_add_u32 s12, s12, 0x8000
	s_addc_u32 s13, s13, 0
	global_load_dwordx4 v[204:207], v171, s[14:15]
	global_load_dwordx4 v[234:237], v171, s[12:13]
	global_load_dwordx4 v[180:183], v170, s[86:87]
	global_load_dwordx4 v[184:187], v170, s[86:87] offset:16
	global_load_dwordx4 v[188:191], v170, s[86:87] offset:128
	global_load_dwordx4 v[192:195], v170, s[86:87] offset:144
	global_load_dwordx4 v[0:3], v170, s[26:27]
	global_load_dwordx4 v[4:7], v170, s[26:27] offset:16
	global_load_dwordx4 v[238:241], v170, s[26:27] offset:128
	global_load_dwordx4 v[242:245], v170, s[26:27] offset:144
	s_waitcnt vmcnt(0)
	v_pk_add_f32 v[182:183], v[182:183], 1.0 op_sel_hi:[1,0]
	v_pk_add_f32 v[180:181], v[180:181], 1.0 op_sel_hi:[1,0]
	v_pk_add_f32 v[186:187], v[186:187], 1.0 op_sel_hi:[1,0]
	v_pk_add_f32 v[184:185], v[184:185], 1.0 op_sel_hi:[1,0]
	v_pk_add_f32 v[190:191], v[190:191], 1.0 op_sel_hi:[1,0]
	v_pk_add_f32 v[188:189], v[188:189], 1.0 op_sel_hi:[1,0]
	v_pk_add_f32 v[194:195], v[194:195], 1.0 op_sel_hi:[1,0]
	v_pk_add_f32 v[192:193], v[192:193], 1.0 op_sel_hi:[1,0]
	v_pk_mul_f32 v[182:183], v[2:3], v[182:183]
	v_pk_mul_f32 v[180:181], v[0:1], v[180:181]
	v_pk_mul_f32 v[186:187], v[6:7], v[186:187]
	v_pk_mul_f32 v[184:185], v[4:5], v[184:185]
	v_pk_mul_f32 v[190:191], v[240:241], v[190:191]
	v_pk_mul_f32 v[188:189], v[238:239], v[188:189]
	v_pk_mul_f32 v[194:195], v[244:245], v[194:195]
	v_pk_mul_f32 v[192:193], v[242:243], v[192:193]
	s_add_u32 s14, s14, 0x8000
	s_addc_u32 s15, s15, 0
	s_add_u32 s12, s12, 0x8000
	s_addc_u32 s13, s13, 0
	global_load_dwordx4 v[238:241], v171, s[14:15]
	global_load_dwordx4 v[242:245], v171, s[12:13]
	s_waitcnt vmcnt(2)
	s_mov_b64 vcc, s[6:7]
	v_cndmask_b32_dpp v0, v200, v196, vcc row_ror:8 row_mask:0xf bank_mask:0xf
	v_cndmask_b32_dpp v1, v201, v197, vcc row_ror:8 row_mask:0xf bank_mask:0xf
	v_cndmask_b32_dpp v2, v202, v198, vcc row_ror:8 row_mask:0xf bank_mask:0xf
	v_cndmask_b32_dpp v3, v203, v199, vcc row_ror:8 row_mask:0xf bank_mask:0xf
	s_not_b64 vcc, s[6:7]
	v_cndmask_b32_dpp v4, v196, v200, vcc row_ror:8 row_mask:0xf bank_mask:0xf
	v_cndmask_b32_dpp v5, v197, v201, vcc row_ror:8 row_mask:0xf bank_mask:0xf
	v_cndmask_b32_dpp v6, v198, v202, vcc row_ror:8 row_mask:0xf bank_mask:0xf
	v_cndmask_b32_dpp v7, v199, v203, vcc row_ror:8 row_mask:0xf bank_mask:0xf
	s_add_u32 s14, s14, 0x8000
	s_addc_u32 s15, s15, 0
	s_add_u32 s12, s12, 0x8000
	s_addc_u32 s13, s13, 0
	global_load_dwordx4 v[196:199], v171, s[14:15]
	global_load_dwordx4 v[200:203], v171, s[12:13]
	v_lshlrev_b32_e32 v246, 16, v0
	v_and_b32_e32 v247, 0xffff0000, v0
	v_pk_fma_f32 v[134:135], v[134:135], v[142:143], v[246:247]
	v_lshlrev_b32_e32 v248, 16, v1
	v_and_b32_e32 v249, 0xffff0000, v1
	v_pk_fma_f32 v[136:137], v[136:137], v[144:145], v[248:249]
	v_lshlrev_b32_e32 v250, 16, v2
	v_and_b32_e32 v251, 0xffff0000, v2
	v_pk_fma_f32 v[130:131], v[130:131], v[150:151], v[250:251]
	v_lshlrev_b32_e32 v208, 16, v3
	v_and_b32_e32 v209, 0xffff0000, v3
	v_pk_fma_f32 v[132:133], v[132:133], v[152:153], v[208:209]
	v_lshlrev_b32_e32 v246, 16, v4
	v_and_b32_e32 v247, 0xffff0000, v4
	v_pk_fma_f32 v[126:127], v[126:127], v[138:139], v[246:247]
	v_lshlrev_b32_e32 v248, 16, v5
	v_and_b32_e32 v249, 0xffff0000, v5
	v_pk_fma_f32 v[128:129], v[128:129], v[140:141], v[248:249]
	v_lshlrev_b32_e32 v250, 16, v6
	v_and_b32_e32 v251, 0xffff0000, v6
	v_pk_fma_f32 v[122:123], v[122:123], v[146:147], v[250:251]
	v_lshlrev_b32_e32 v208, 16, v7
	v_and_b32_e32 v209, 0xffff0000, v7
	v_pk_fma_f32 v[124:125], v[124:125], v[148:149], v[208:209]
	v_cvt_pk_bf16_f32 v0, v134, v135
	v_cvt_pk_bf16_f32 v1, v136, v137
	v_cvt_pk_bf16_f32 v2, v130, v131
	v_cvt_pk_bf16_f32 v3, v132, v133
	v_cvt_pk_bf16_f32 v4, v126, v127
	v_cvt_pk_bf16_f32 v5, v128, v129
	v_cvt_pk_bf16_f32 v6, v122, v123
	v_cvt_pk_bf16_f32 v7, v124, v125
	v_mul_f32_e32 v246, v135, v135
	v_mul_f32_e32 v248, v137, v137
	v_fmac_f32_e32 v246, v134, v134
	v_fmac_f32_e32 v248, v136, v136
	v_add_f32_e32 v246, v246, v248
	v_mul_f32_e32 v248, v131, v131
	v_fmac_f32_e32 v248, v130, v130
	v_add_f32_e32 v246, v246, v248
	v_mul_f32_e32 v248, v133, v133
	v_fmac_f32_e32 v248, v132, v132
	v_add_f32_e32 v246, v248, v246
	v_mul_f32_e32 v247, v127, v127
	v_mul_f32_e32 v248, v129, v129
	v_fmac_f32_e32 v247, v126, v126
	v_fmac_f32_e32 v248, v128, v128
	v_add_f32_e32 v247, v247, v248
	v_mul_f32_e32 v248, v123, v123
	v_fmac_f32_e32 v248, v122, v122
	v_add_f32_e32 v247, v247, v248
	v_mul_f32_e32 v248, v125, v125
	v_fmac_f32_e32 v248, v124, v124
	v_add_f32_e32 v247, v248, v247
	v_add_f32_e32 v246, v246, v247
	v_mov_b32_e32 v247, v246
	s_nop 1
	v_permlane16_swap_b32_e32 v246, v247
	s_nop 1
	v_add_f32_e32 v246, v246, v247
	v_mov_b32_e32 v247, v246
	s_nop 1
	v_permlane32_swap_b32_e32 v246, v247
	v_add_u32_e32 v248, s8, v223
	s_nop 0
	v_add_f32_e32 v246, v246, v247
	s_mov_b64 exec, s[44:45]
	ds_write_b32 v248, v246
	s_mov_b64 exec, -1
	v_pk_mul_f32 v[134:135], v[180:181], v[134:135]
	v_pk_mul_f32 v[136:137], v[182:183], v[136:137]
	v_pk_mul_f32 v[130:131], v[184:185], v[130:131]
	v_pk_mul_f32 v[132:133], v[186:187], v[132:133]
	v_pk_mul_f32 v[126:127], v[188:189], v[126:127]
	v_pk_mul_f32 v[128:129], v[190:191], v[128:129]
	v_pk_mul_f32 v[122:123], v[192:193], v[122:123]
	v_pk_mul_f32 v[124:125], v[194:195], v[124:125]
	v_cvt_pk_bf16_f32 v246, v134, v135
	v_cvt_pk_bf16_f32 v247, v136, v137
	v_cvt_pk_bf16_f32 v248, v130, v131
	v_cvt_pk_bf16_f32 v249, v132, v133
	v_cvt_pk_bf16_f32 v250, v126, v127
	v_cvt_pk_bf16_f32 v251, v128, v129
	v_cvt_pk_bf16_f32 v208, v122, v123
	v_cvt_pk_bf16_f32 v209, v124, v125
	s_nop 1
	s_mov_b64 vcc, s[6:7]
	v_cndmask_b32_dpp v134, v4, v0, vcc row_ror:8 row_mask:0xf bank_mask:0xf
	v_cndmask_b32_dpp v135, v5, v1, vcc row_ror:8 row_mask:0xf bank_mask:0xf
	v_cndmask_b32_dpp v136, v6, v2, vcc row_ror:8 row_mask:0xf bank_mask:0xf
	v_cndmask_b32_dpp v137, v7, v3, vcc row_ror:8 row_mask:0xf bank_mask:0xf
	v_cndmask_b32_dpp v126, v250, v246, vcc row_ror:8 row_mask:0xf bank_mask:0xf
	v_cndmask_b32_dpp v127, v251, v247, vcc row_ror:8 row_mask:0xf bank_mask:0xf
	v_cndmask_b32_dpp v128, v208, v248, vcc row_ror:8 row_mask:0xf bank_mask:0xf
	v_cndmask_b32_dpp v129, v209, v249, vcc row_ror:8 row_mask:0xf bank_mask:0xf
	s_not_b64 vcc, s[6:7]
	v_cndmask_b32_dpp v130, v0, v4, vcc row_ror:8 row_mask:0xf bank_mask:0xf
	v_cndmask_b32_dpp v131, v1, v5, vcc row_ror:8 row_mask:0xf bank_mask:0xf
	v_cndmask_b32_dpp v132, v2, v6, vcc row_ror:8 row_mask:0xf bank_mask:0xf
	v_cndmask_b32_dpp v133, v3, v7, vcc row_ror:8 row_mask:0xf bank_mask:0xf
	v_cndmask_b32_dpp v122, v246, v250, vcc row_ror:8 row_mask:0xf bank_mask:0xf
	v_cndmask_b32_dpp v123, v247, v251, vcc row_ror:8 row_mask:0xf bank_mask:0xf
	v_cndmask_b32_dpp v124, v248, v208, vcc row_ror:8 row_mask:0xf bank_mask:0xf
	v_cndmask_b32_dpp v125, v249, v209, vcc row_ror:8 row_mask:0xf bank_mask:0xf
	global_store_dwordx4 v171, v[134:137], s[2:3] nt
	global_store_dwordx4 v171, v[130:133], s[18:19] nt
	global_store_dwordx4 v171, v[126:129], s[78:79]
	global_store_dwordx4 v171, v[122:125], s[22:23]
	s_waitcnt vmcnt(8)
	s_mov_b64 vcc, s[6:7]
	v_cndmask_b32_dpp v0, v234, v204, vcc row_ror:8 row_mask:0xf bank_mask:0xf
	v_cndmask_b32_dpp v1, v235, v205, vcc row_ror:8 row_mask:0xf bank_mask:0xf
	v_cndmask_b32_dpp v2, v236, v206, vcc row_ror:8 row_mask:0xf bank_mask:0xf
	v_cndmask_b32_dpp v3, v237, v207, vcc row_ror:8 row_mask:0xf bank_mask:0xf
	s_not_b64 vcc, s[6:7]
	v_cndmask_b32_dpp v4, v204, v234, vcc row_ror:8 row_mask:0xf bank_mask:0xf
	v_cndmask_b32_dpp v5, v205, v235, vcc row_ror:8 row_mask:0xf bank_mask:0xf
	v_cndmask_b32_dpp v6, v206, v236, vcc row_ror:8 row_mask:0xf bank_mask:0xf
	v_cndmask_b32_dpp v7, v207, v237, vcc row_ror:8 row_mask:0xf bank_mask:0xf
	s_add_u32 s14, s14, 0x28000
	s_addc_u32 s15, s15, 0
	s_add_u32 s12, s12, 0x28000
	s_addc_u32 s13, s13, 0
	global_load_dwordx4 v[204:207], v171, s[14:15]
	global_load_dwordx4 v[234:237], v171, s[12:13]
	v_lshlrev_b32_e32 v246, 16, v0
	v_and_b32_e32 v247, 0xffff0000, v0
	v_pk_fma_f32 v[118:119], v[118:119], v[142:143], v[246:247]
	v_lshlrev_b32_e32 v248, 16, v1
	v_and_b32_e32 v249, 0xffff0000, v1
	v_pk_fma_f32 v[120:121], v[120:121], v[144:145], v[248:249]
	v_lshlrev_b32_e32 v250, 16, v2
	v_and_b32_e32 v251, 0xffff0000, v2
	v_pk_fma_f32 v[114:115], v[114:115], v[150:151], v[250:251]
	v_lshlrev_b32_e32 v208, 16, v3
	v_and_b32_e32 v209, 0xffff0000, v3
	v_pk_fma_f32 v[116:117], v[116:117], v[152:153], v[208:209]
	v_lshlrev_b32_e32 v246, 16, v4
	v_and_b32_e32 v247, 0xffff0000, v4
	v_pk_fma_f32 v[110:111], v[110:111], v[138:139], v[246:247]
	v_lshlrev_b32_e32 v248, 16, v5
	v_and_b32_e32 v249, 0xffff0000, v5
	v_pk_fma_f32 v[112:113], v[112:113], v[140:141], v[248:249]
	v_lshlrev_b32_e32 v250, 16, v6
	v_and_b32_e32 v251, 0xffff0000, v6
	v_pk_fma_f32 v[106:107], v[106:107], v[146:147], v[250:251]
	v_lshlrev_b32_e32 v208, 16, v7
	v_and_b32_e32 v209, 0xffff0000, v7
	v_pk_fma_f32 v[108:109], v[108:109], v[148:149], v[208:209]
	v_cvt_pk_bf16_f32 v0, v118, v119
	v_cvt_pk_bf16_f32 v1, v120, v121
	v_cvt_pk_bf16_f32 v2, v114, v115
	v_cvt_pk_bf16_f32 v3, v116, v117
	v_cvt_pk_bf16_f32 v4, v110, v111
	v_cvt_pk_bf16_f32 v5, v112, v113
	v_cvt_pk_bf16_f32 v6, v106, v107
	v_cvt_pk_bf16_f32 v7, v108, v109
	v_mul_f32_e32 v246, v119, v119
	v_mul_f32_e32 v248, v121, v121
	v_fmac_f32_e32 v246, v118, v118
	v_fmac_f32_e32 v248, v120, v120
	v_add_f32_e32 v246, v246, v248
	v_mul_f32_e32 v248, v115, v115
	v_fmac_f32_e32 v248, v114, v114
	v_add_f32_e32 v246, v246, v248
	v_mul_f32_e32 v248, v117, v117
	v_fmac_f32_e32 v248, v116, v116
	v_add_f32_e32 v246, v248, v246
	v_mul_f32_e32 v247, v111, v111
	v_mul_f32_e32 v248, v113, v113
	v_fmac_f32_e32 v247, v110, v110
	v_fmac_f32_e32 v248, v112, v112
	v_add_f32_e32 v247, v247, v248
	v_mul_f32_e32 v248, v107, v107
	v_fmac_f32_e32 v248, v106, v106
	v_add_f32_e32 v247, v247, v248
	v_mul_f32_e32 v248, v109, v109
	v_fmac_f32_e32 v248, v108, v108
	v_add_f32_e32 v247, v248, v247
	v_add_f32_e32 v246, v246, v247
	v_mov_b32_e32 v247, v246
	s_nop 1
	v_permlane16_swap_b32_e32 v246, v247
	s_nop 1
	v_add_f32_e32 v246, v246, v247
	v_mov_b32_e32 v247, v246
	s_nop 1
	v_permlane32_swap_b32_e32 v246, v247
	v_add_u32_e32 v248, s8, v223
	s_nop 0
	v_add_f32_e32 v246, v246, v247
	s_mov_b64 exec, s[44:45]
	ds_write_b32 v248, v246 offset:256
	s_mov_b64 exec, -1
	v_pk_mul_f32 v[118:119], v[180:181], v[118:119]
	v_pk_mul_f32 v[120:121], v[182:183], v[120:121]
	v_pk_mul_f32 v[114:115], v[184:185], v[114:115]
	v_pk_mul_f32 v[116:117], v[186:187], v[116:117]
	v_pk_mul_f32 v[110:111], v[188:189], v[110:111]
	v_pk_mul_f32 v[112:113], v[190:191], v[112:113]
	v_pk_mul_f32 v[106:107], v[192:193], v[106:107]
	v_pk_mul_f32 v[108:109], v[194:195], v[108:109]
	v_cvt_pk_bf16_f32 v246, v118, v119
	v_cvt_pk_bf16_f32 v247, v120, v121
	v_cvt_pk_bf16_f32 v248, v114, v115
	v_cvt_pk_bf16_f32 v249, v116, v117
	v_cvt_pk_bf16_f32 v250, v110, v111
	v_cvt_pk_bf16_f32 v251, v112, v113
	v_cvt_pk_bf16_f32 v208, v106, v107
	v_cvt_pk_bf16_f32 v209, v108, v109
	s_add_u32 s2, s2, 0x8000
	s_addc_u32 s3, s3, 0
	s_add_u32 s18, s18, 0x8000
	s_addc_u32 s19, s19, 0
	s_add_u32 s78, s78, 0x8000
	s_addc_u32 s79, s79, 0
	s_add_u32 s22, s22, 0x8000
	s_addc_u32 s23, s23, 0
	s_mov_b64 vcc, s[6:7]
	v_cndmask_b32_dpp v118, v4, v0, vcc row_ror:8 row_mask:0xf bank_mask:0xf
	v_cndmask_b32_dpp v119, v5, v1, vcc row_ror:8 row_mask:0xf bank_mask:0xf
	v_cndmask_b32_dpp v120, v6, v2, vcc row_ror:8 row_mask:0xf bank_mask:0xf
	v_cndmask_b32_dpp v121, v7, v3, vcc row_ror:8 row_mask:0xf bank_mask:0xf
	v_cndmask_b32_dpp v110, v250, v246, vcc row_ror:8 row_mask:0xf bank_mask:0xf
	v_cndmask_b32_dpp v111, v251, v247, vcc row_ror:8 row_mask:0xf bank_mask:0xf
	v_cndmask_b32_dpp v112, v208, v248, vcc row_ror:8 row_mask:0xf bank_mask:0xf
	v_cndmask_b32_dpp v113, v209, v249, vcc row_ror:8 row_mask:0xf bank_mask:0xf
	s_not_b64 vcc, s[6:7]
	v_cndmask_b32_dpp v114, v0, v4, vcc row_ror:8 row_mask:0xf bank_mask:0xf
	v_cndmask_b32_dpp v115, v1, v5, vcc row_ror:8 row_mask:0xf bank_mask:0xf
	v_cndmask_b32_dpp v116, v2, v6, vcc row_ror:8 row_mask:0xf bank_mask:0xf
	v_cndmask_b32_dpp v117, v3, v7, vcc row_ror:8 row_mask:0xf bank_mask:0xf
	v_cndmask_b32_dpp v106, v246, v250, vcc row_ror:8 row_mask:0xf bank_mask:0xf
	v_cndmask_b32_dpp v107, v247, v251, vcc row_ror:8 row_mask:0xf bank_mask:0xf
	v_cndmask_b32_dpp v108, v248, v208, vcc row_ror:8 row_mask:0xf bank_mask:0xf
	v_cndmask_b32_dpp v109, v249, v209, vcc row_ror:8 row_mask:0xf bank_mask:0xf
	global_store_dwordx4 v171, v[118:121], s[2:3] nt
	global_store_dwordx4 v171, v[114:117], s[18:19] nt
	global_store_dwordx4 v171, v[110:113], s[78:79]
	global_store_dwordx4 v171, v[106:109], s[22:23]
	s_waitcnt vmcnt(12)
	s_mov_b64 vcc, s[6:7]
	v_cndmask_b32_dpp v0, v242, v238, vcc row_ror:8 row_mask:0xf bank_mask:0xf
	v_cndmask_b32_dpp v1, v243, v239, vcc row_ror:8 row_mask:0xf bank_mask:0xf
	v_cndmask_b32_dpp v2, v244, v240, vcc row_ror:8 row_mask:0xf bank_mask:0xf
	v_cndmask_b32_dpp v3, v245, v241, vcc row_ror:8 row_mask:0xf bank_mask:0xf
	s_not_b64 vcc, s[6:7]
	v_cndmask_b32_dpp v4, v238, v242, vcc row_ror:8 row_mask:0xf bank_mask:0xf
	v_cndmask_b32_dpp v5, v239, v243, vcc row_ror:8 row_mask:0xf bank_mask:0xf
	v_cndmask_b32_dpp v6, v240, v244, vcc row_ror:8 row_mask:0xf bank_mask:0xf
	v_cndmask_b32_dpp v7, v241, v245, vcc row_ror:8 row_mask:0xf bank_mask:0xf
	s_add_u32 s14, s14, 0x8000
	s_addc_u32 s15, s15, 0
	s_add_u32 s12, s12, 0x8000
	s_addc_u32 s13, s13, 0
	global_load_dwordx4 v[238:241], v171, s[14:15]
	global_load_dwordx4 v[242:245], v171, s[12:13]
	v_lshlrev_b32_e32 v246, 16, v0
	v_and_b32_e32 v247, 0xffff0000, v0
	v_pk_fma_f32 v[102:103], v[102:103], v[142:143], v[246:247]
	v_lshlrev_b32_e32 v248, 16, v1
	v_and_b32_e32 v249, 0xffff0000, v1
	v_pk_fma_f32 v[104:105], v[104:105], v[144:145], v[248:249]
	v_lshlrev_b32_e32 v250, 16, v2
	v_and_b32_e32 v251, 0xffff0000, v2
	v_pk_fma_f32 v[98:99], v[98:99], v[150:151], v[250:251]
	v_lshlrev_b32_e32 v208, 16, v3
	v_and_b32_e32 v209, 0xffff0000, v3
	v_pk_fma_f32 v[100:101], v[100:101], v[152:153], v[208:209]
	v_lshlrev_b32_e32 v246, 16, v4
	v_and_b32_e32 v247, 0xffff0000, v4
	v_pk_fma_f32 v[92:93], v[92:93], v[138:139], v[246:247]
	v_lshlrev_b32_e32 v248, 16, v5
	v_and_b32_e32 v249, 0xffff0000, v5
	v_pk_fma_f32 v[94:95], v[94:95], v[140:141], v[248:249]
	v_lshlrev_b32_e32 v250, 16, v6
	v_and_b32_e32 v251, 0xffff0000, v6
	v_pk_fma_f32 v[88:89], v[88:89], v[146:147], v[250:251]
	v_lshlrev_b32_e32 v208, 16, v7
	v_and_b32_e32 v209, 0xffff0000, v7
	v_pk_fma_f32 v[90:91], v[90:91], v[148:149], v[208:209]
	v_cvt_pk_bf16_f32 v0, v102, v103
	v_cvt_pk_bf16_f32 v1, v104, v105
	v_cvt_pk_bf16_f32 v2, v98, v99
	v_cvt_pk_bf16_f32 v3, v100, v101
	v_cvt_pk_bf16_f32 v4, v92, v93
	v_cvt_pk_bf16_f32 v5, v94, v95
	v_cvt_pk_bf16_f32 v6, v88, v89
	v_cvt_pk_bf16_f32 v7, v90, v91
	v_mul_f32_e32 v246, v103, v103
	v_mul_f32_e32 v248, v105, v105
	v_fmac_f32_e32 v246, v102, v102
	v_fmac_f32_e32 v248, v104, v104
	v_add_f32_e32 v246, v246, v248
	v_mul_f32_e32 v248, v99, v99
	v_fmac_f32_e32 v248, v98, v98
	v_add_f32_e32 v246, v246, v248
	v_mul_f32_e32 v248, v101, v101
	v_fmac_f32_e32 v248, v100, v100
	v_add_f32_e32 v246, v248, v246
	v_mul_f32_e32 v247, v93, v93
	v_mul_f32_e32 v248, v95, v95
	v_fmac_f32_e32 v247, v92, v92
	v_fmac_f32_e32 v248, v94, v94
	v_add_f32_e32 v247, v247, v248
	v_mul_f32_e32 v248, v89, v89
	v_fmac_f32_e32 v248, v88, v88
	v_add_f32_e32 v247, v247, v248
	v_mul_f32_e32 v248, v91, v91
	v_fmac_f32_e32 v248, v90, v90
	v_add_f32_e32 v247, v248, v247
	v_add_f32_e32 v246, v246, v247
	v_mov_b32_e32 v247, v246
	s_nop 1
	v_permlane16_swap_b32_e32 v246, v247
	s_nop 1
	v_add_f32_e32 v246, v246, v247
	v_mov_b32_e32 v247, v246
	s_nop 1
	v_permlane32_swap_b32_e32 v246, v247
	v_add_u32_e32 v248, s8, v223
	s_nop 0
	v_add_f32_e32 v246, v246, v247
	s_mov_b64 exec, s[44:45]
	ds_write_b32 v248, v246 offset:512
	s_mov_b64 exec, -1
	v_pk_mul_f32 v[102:103], v[180:181], v[102:103]
	v_pk_mul_f32 v[104:105], v[182:183], v[104:105]
	v_pk_mul_f32 v[98:99], v[184:185], v[98:99]
	v_pk_mul_f32 v[100:101], v[186:187], v[100:101]
	v_pk_mul_f32 v[92:93], v[188:189], v[92:93]
	v_pk_mul_f32 v[94:95], v[190:191], v[94:95]
	v_pk_mul_f32 v[88:89], v[192:193], v[88:89]
	v_pk_mul_f32 v[90:91], v[194:195], v[90:91]
	v_cvt_pk_bf16_f32 v246, v102, v103
	v_cvt_pk_bf16_f32 v247, v104, v105
	v_cvt_pk_bf16_f32 v248, v98, v99
	v_cvt_pk_bf16_f32 v249, v100, v101
	v_cvt_pk_bf16_f32 v250, v92, v93
	v_cvt_pk_bf16_f32 v251, v94, v95
	v_cvt_pk_bf16_f32 v208, v88, v89
	v_cvt_pk_bf16_f32 v209, v90, v91
	s_add_u32 s2, s2, 0x8000
	s_addc_u32 s3, s3, 0
	s_add_u32 s18, s18, 0x8000
	s_addc_u32 s19, s19, 0
	s_add_u32 s78, s78, 0x8000
	s_addc_u32 s79, s79, 0
	s_add_u32 s22, s22, 0x8000
	s_addc_u32 s23, s23, 0
	s_mov_b64 vcc, s[6:7]
	v_cndmask_b32_dpp v102, v4, v0, vcc row_ror:8 row_mask:0xf bank_mask:0xf
	v_cndmask_b32_dpp v103, v5, v1, vcc row_ror:8 row_mask:0xf bank_mask:0xf
	v_cndmask_b32_dpp v104, v6, v2, vcc row_ror:8 row_mask:0xf bank_mask:0xf
	v_cndmask_b32_dpp v105, v7, v3, vcc row_ror:8 row_mask:0xf bank_mask:0xf
	v_cndmask_b32_dpp v92, v250, v246, vcc row_ror:8 row_mask:0xf bank_mask:0xf
	v_cndmask_b32_dpp v93, v251, v247, vcc row_ror:8 row_mask:0xf bank_mask:0xf
	v_cndmask_b32_dpp v94, v208, v248, vcc row_ror:8 row_mask:0xf bank_mask:0xf
	v_cndmask_b32_dpp v95, v209, v249, vcc row_ror:8 row_mask:0xf bank_mask:0xf
	s_not_b64 vcc, s[6:7]
	v_cndmask_b32_dpp v98, v0, v4, vcc row_ror:8 row_mask:0xf bank_mask:0xf
	v_cndmask_b32_dpp v99, v1, v5, vcc row_ror:8 row_mask:0xf bank_mask:0xf
	v_cndmask_b32_dpp v100, v2, v6, vcc row_ror:8 row_mask:0xf bank_mask:0xf
	v_cndmask_b32_dpp v101, v3, v7, vcc row_ror:8 row_mask:0xf bank_mask:0xf
	v_cndmask_b32_dpp v88, v246, v250, vcc row_ror:8 row_mask:0xf bank_mask:0xf
	v_cndmask_b32_dpp v89, v247, v251, vcc row_ror:8 row_mask:0xf bank_mask:0xf
	v_cndmask_b32_dpp v90, v248, v208, vcc row_ror:8 row_mask:0xf bank_mask:0xf
	v_cndmask_b32_dpp v91, v249, v209, vcc row_ror:8 row_mask:0xf bank_mask:0xf
	global_store_dwordx4 v171, v[102:105], s[2:3] nt
	global_store_dwordx4 v171, v[98:101], s[18:19] nt
	global_store_dwordx4 v171, v[92:95], s[78:79]
	global_store_dwordx4 v171, v[88:91], s[22:23]
	s_waitcnt vmcnt(16)
	s_mov_b64 vcc, s[6:7]
	v_cndmask_b32_dpp v0, v200, v196, vcc row_ror:8 row_mask:0xf bank_mask:0xf
	v_cndmask_b32_dpp v1, v201, v197, vcc row_ror:8 row_mask:0xf bank_mask:0xf
	v_cndmask_b32_dpp v2, v202, v198, vcc row_ror:8 row_mask:0xf bank_mask:0xf
	v_cndmask_b32_dpp v3, v203, v199, vcc row_ror:8 row_mask:0xf bank_mask:0xf
	s_not_b64 vcc, s[6:7]
	v_cndmask_b32_dpp v4, v196, v200, vcc row_ror:8 row_mask:0xf bank_mask:0xf
	v_cndmask_b32_dpp v5, v197, v201, vcc row_ror:8 row_mask:0xf bank_mask:0xf
	v_cndmask_b32_dpp v6, v198, v202, vcc row_ror:8 row_mask:0xf bank_mask:0xf
	v_cndmask_b32_dpp v7, v199, v203, vcc row_ror:8 row_mask:0xf bank_mask:0xf
	s_add_u32 s14, s14, 0x8000
	s_addc_u32 s15, s15, 0
	s_add_u32 s12, s12, 0x8000
	s_addc_u32 s13, s13, 0
	global_load_dwordx4 v[196:199], v171, s[14:15]
	global_load_dwordx4 v[200:203], v171, s[12:13]
	v_lshlrev_b32_e32 v246, 16, v0
	v_and_b32_e32 v247, 0xffff0000, v0
	v_pk_fma_f32 v[84:85], v[84:85], v[142:143], v[246:247]
	v_lshlrev_b32_e32 v248, 16, v1
	v_and_b32_e32 v249, 0xffff0000, v1
	v_pk_fma_f32 v[86:87], v[86:87], v[144:145], v[248:249]
	v_lshlrev_b32_e32 v250, 16, v2
	v_and_b32_e32 v251, 0xffff0000, v2
	v_pk_fma_f32 v[80:81], v[80:81], v[150:151], v[250:251]
	v_lshlrev_b32_e32 v208, 16, v3
	v_and_b32_e32 v209, 0xffff0000, v3
	v_pk_fma_f32 v[82:83], v[82:83], v[152:153], v[208:209]
	v_lshlrev_b32_e32 v246, 16, v4
	v_and_b32_e32 v247, 0xffff0000, v4
	v_pk_fma_f32 v[76:77], v[76:77], v[138:139], v[246:247]
	v_lshlrev_b32_e32 v248, 16, v5
	v_and_b32_e32 v249, 0xffff0000, v5
	v_pk_fma_f32 v[78:79], v[78:79], v[140:141], v[248:249]
	v_lshlrev_b32_e32 v250, 16, v6
	v_and_b32_e32 v251, 0xffff0000, v6
	v_pk_fma_f32 v[72:73], v[72:73], v[146:147], v[250:251]
	v_lshlrev_b32_e32 v208, 16, v7
	v_and_b32_e32 v209, 0xffff0000, v7
	v_pk_fma_f32 v[74:75], v[74:75], v[148:149], v[208:209]
	v_cvt_pk_bf16_f32 v0, v84, v85
	v_cvt_pk_bf16_f32 v1, v86, v87
	v_cvt_pk_bf16_f32 v2, v80, v81
	v_cvt_pk_bf16_f32 v3, v82, v83
	v_cvt_pk_bf16_f32 v4, v76, v77
	v_cvt_pk_bf16_f32 v5, v78, v79
	v_cvt_pk_bf16_f32 v6, v72, v73
	v_cvt_pk_bf16_f32 v7, v74, v75
	v_mul_f32_e32 v246, v85, v85
	v_mul_f32_e32 v248, v87, v87
	v_fmac_f32_e32 v246, v84, v84
	v_fmac_f32_e32 v248, v86, v86
	v_add_f32_e32 v246, v246, v248
	v_mul_f32_e32 v248, v81, v81
	v_fmac_f32_e32 v248, v80, v80
	v_add_f32_e32 v246, v246, v248
	v_mul_f32_e32 v248, v83, v83
	v_fmac_f32_e32 v248, v82, v82
	v_add_f32_e32 v246, v248, v246
	v_mul_f32_e32 v247, v77, v77
	v_mul_f32_e32 v248, v79, v79
	v_fmac_f32_e32 v247, v76, v76
	v_fmac_f32_e32 v248, v78, v78
	v_add_f32_e32 v247, v247, v248
	v_mul_f32_e32 v248, v73, v73
	v_fmac_f32_e32 v248, v72, v72
	v_add_f32_e32 v247, v247, v248
	v_mul_f32_e32 v248, v75, v75
	v_fmac_f32_e32 v248, v74, v74
	v_add_f32_e32 v247, v248, v247
	v_add_f32_e32 v246, v246, v247
	v_mov_b32_e32 v247, v246
	s_nop 1
	v_permlane16_swap_b32_e32 v246, v247
	s_nop 1
	v_add_f32_e32 v246, v246, v247
	v_mov_b32_e32 v247, v246
	s_nop 1
	v_permlane32_swap_b32_e32 v246, v247
	v_add_u32_e32 v248, s8, v223
	s_nop 0
	v_add_f32_e32 v246, v246, v247
	s_mov_b64 exec, s[44:45]
	ds_write_b32 v248, v246 offset:768
	s_mov_b64 exec, -1
	v_pk_mul_f32 v[84:85], v[180:181], v[84:85]
	v_pk_mul_f32 v[86:87], v[182:183], v[86:87]
	v_pk_mul_f32 v[80:81], v[184:185], v[80:81]
	v_pk_mul_f32 v[82:83], v[186:187], v[82:83]
	v_pk_mul_f32 v[76:77], v[188:189], v[76:77]
	v_pk_mul_f32 v[78:79], v[190:191], v[78:79]
	v_pk_mul_f32 v[72:73], v[192:193], v[72:73]
	v_pk_mul_f32 v[74:75], v[194:195], v[74:75]
	v_cvt_pk_bf16_f32 v246, v84, v85
	v_cvt_pk_bf16_f32 v247, v86, v87
	v_cvt_pk_bf16_f32 v248, v80, v81
	v_cvt_pk_bf16_f32 v249, v82, v83
	v_cvt_pk_bf16_f32 v250, v76, v77
	v_cvt_pk_bf16_f32 v251, v78, v79
	v_cvt_pk_bf16_f32 v208, v72, v73
	v_cvt_pk_bf16_f32 v209, v74, v75
	s_add_u32 s2, s2, 0x8000
	s_addc_u32 s3, s3, 0
	s_add_u32 s18, s18, 0x8000
	s_addc_u32 s19, s19, 0
	s_add_u32 s78, s78, 0x8000
	s_addc_u32 s79, s79, 0
	s_add_u32 s22, s22, 0x8000
	s_addc_u32 s23, s23, 0
	s_mov_b64 vcc, s[6:7]
	v_cndmask_b32_dpp v84, v4, v0, vcc row_ror:8 row_mask:0xf bank_mask:0xf
	v_cndmask_b32_dpp v85, v5, v1, vcc row_ror:8 row_mask:0xf bank_mask:0xf
	v_cndmask_b32_dpp v86, v6, v2, vcc row_ror:8 row_mask:0xf bank_mask:0xf
	v_cndmask_b32_dpp v87, v7, v3, vcc row_ror:8 row_mask:0xf bank_mask:0xf
	v_cndmask_b32_dpp v76, v250, v246, vcc row_ror:8 row_mask:0xf bank_mask:0xf
	v_cndmask_b32_dpp v77, v251, v247, vcc row_ror:8 row_mask:0xf bank_mask:0xf
	v_cndmask_b32_dpp v78, v208, v248, vcc row_ror:8 row_mask:0xf bank_mask:0xf
	v_cndmask_b32_dpp v79, v209, v249, vcc row_ror:8 row_mask:0xf bank_mask:0xf
	s_not_b64 vcc, s[6:7]
	v_cndmask_b32_dpp v80, v0, v4, vcc row_ror:8 row_mask:0xf bank_mask:0xf
	v_cndmask_b32_dpp v81, v1, v5, vcc row_ror:8 row_mask:0xf bank_mask:0xf
	v_cndmask_b32_dpp v82, v2, v6, vcc row_ror:8 row_mask:0xf bank_mask:0xf
	v_cndmask_b32_dpp v83, v3, v7, vcc row_ror:8 row_mask:0xf bank_mask:0xf
	v_cndmask_b32_dpp v72, v246, v250, vcc row_ror:8 row_mask:0xf bank_mask:0xf
	v_cndmask_b32_dpp v73, v247, v251, vcc row_ror:8 row_mask:0xf bank_mask:0xf
	v_cndmask_b32_dpp v74, v248, v208, vcc row_ror:8 row_mask:0xf bank_mask:0xf
	v_cndmask_b32_dpp v75, v249, v209, vcc row_ror:8 row_mask:0xf bank_mask:0xf
	global_store_dwordx4 v171, v[84:87], s[2:3] nt
	global_store_dwordx4 v171, v[80:83], s[18:19] nt
	global_store_dwordx4 v171, v[76:79], s[78:79]
	global_store_dwordx4 v171, v[72:75], s[22:23]
	s_waitcnt vmcnt(16)
	s_mov_b64 vcc, s[6:7]
	v_cndmask_b32_dpp v0, v234, v204, vcc row_ror:8 row_mask:0xf bank_mask:0xf
	v_cndmask_b32_dpp v1, v235, v205, vcc row_ror:8 row_mask:0xf bank_mask:0xf
	v_cndmask_b32_dpp v2, v236, v206, vcc row_ror:8 row_mask:0xf bank_mask:0xf
	v_cndmask_b32_dpp v3, v237, v207, vcc row_ror:8 row_mask:0xf bank_mask:0xf
	s_not_b64 vcc, s[6:7]
	v_cndmask_b32_dpp v4, v204, v234, vcc row_ror:8 row_mask:0xf bank_mask:0xf
	v_cndmask_b32_dpp v5, v205, v235, vcc row_ror:8 row_mask:0xf bank_mask:0xf
	v_cndmask_b32_dpp v6, v206, v236, vcc row_ror:8 row_mask:0xf bank_mask:0xf
	v_cndmask_b32_dpp v7, v207, v237, vcc row_ror:8 row_mask:0xf bank_mask:0xf
	s_add_u32 s14, s14, 0x8000
	s_addc_u32 s15, s15, 0
	s_add_u32 s12, s12, 0x8000
	s_addc_u32 s13, s13, 0
	global_load_dwordx4 v[204:207], v171, s[14:15]
	global_load_dwordx4 v[234:237], v171, s[12:13]
	v_lshlrev_b32_e32 v246, 16, v0
	v_and_b32_e32 v247, 0xffff0000, v0
	v_pk_fma_f32 v[68:69], v[68:69], v[142:143], v[246:247]
	v_lshlrev_b32_e32 v248, 16, v1
	v_and_b32_e32 v249, 0xffff0000, v1
	v_pk_fma_f32 v[70:71], v[70:71], v[144:145], v[248:249]
	v_lshlrev_b32_e32 v250, 16, v2
	v_and_b32_e32 v251, 0xffff0000, v2
	v_pk_fma_f32 v[64:65], v[64:65], v[150:151], v[250:251]
	v_lshlrev_b32_e32 v208, 16, v3
	v_and_b32_e32 v209, 0xffff0000, v3
	v_pk_fma_f32 v[66:67], v[66:67], v[152:153], v[208:209]
	v_lshlrev_b32_e32 v246, 16, v4
	v_and_b32_e32 v247, 0xffff0000, v4
	v_pk_fma_f32 v[60:61], v[60:61], v[138:139], v[246:247]
	v_lshlrev_b32_e32 v248, 16, v5
	v_and_b32_e32 v249, 0xffff0000, v5
	v_pk_fma_f32 v[62:63], v[62:63], v[140:141], v[248:249]
	v_lshlrev_b32_e32 v250, 16, v6
	v_and_b32_e32 v251, 0xffff0000, v6
	v_pk_fma_f32 v[56:57], v[56:57], v[146:147], v[250:251]
	v_lshlrev_b32_e32 v208, 16, v7
	v_and_b32_e32 v209, 0xffff0000, v7
	v_pk_fma_f32 v[58:59], v[58:59], v[148:149], v[208:209]
	v_cvt_pk_bf16_f32 v0, v68, v69
	v_cvt_pk_bf16_f32 v1, v70, v71
	v_cvt_pk_bf16_f32 v2, v64, v65
	v_cvt_pk_bf16_f32 v3, v66, v67
	v_cvt_pk_bf16_f32 v4, v60, v61
	v_cvt_pk_bf16_f32 v5, v62, v63
	v_cvt_pk_bf16_f32 v6, v56, v57
	v_cvt_pk_bf16_f32 v7, v58, v59
	v_mul_f32_e32 v246, v69, v69
	v_mul_f32_e32 v248, v71, v71
	v_fmac_f32_e32 v246, v68, v68
	v_fmac_f32_e32 v248, v70, v70
	v_add_f32_e32 v246, v246, v248
	v_mul_f32_e32 v248, v65, v65
	v_fmac_f32_e32 v248, v64, v64
	v_add_f32_e32 v246, v246, v248
	v_mul_f32_e32 v248, v67, v67
	v_fmac_f32_e32 v248, v66, v66
	v_add_f32_e32 v246, v248, v246
	v_mul_f32_e32 v247, v61, v61
	v_mul_f32_e32 v248, v63, v63
	v_fmac_f32_e32 v247, v60, v60
	v_fmac_f32_e32 v248, v62, v62
	v_add_f32_e32 v247, v247, v248
	v_mul_f32_e32 v248, v57, v57
	v_fmac_f32_e32 v248, v56, v56
	v_add_f32_e32 v247, v247, v248
	v_mul_f32_e32 v248, v59, v59
	v_fmac_f32_e32 v248, v58, v58
	v_add_f32_e32 v247, v248, v247
	v_add_f32_e32 v246, v246, v247
	v_mov_b32_e32 v247, v246
	s_nop 1
	v_permlane16_swap_b32_e32 v246, v247
	s_nop 1
	v_add_f32_e32 v246, v246, v247
	v_mov_b32_e32 v247, v246
	s_nop 1
	v_permlane32_swap_b32_e32 v246, v247
	v_add_u32_e32 v248, s8, v223
	s_nop 0
	v_add_f32_e32 v246, v246, v247
	s_mov_b64 exec, s[44:45]
	ds_write_b32 v248, v246 offset:2048
	s_mov_b64 exec, -1
	v_pk_mul_f32 v[68:69], v[180:181], v[68:69]
	v_pk_mul_f32 v[70:71], v[182:183], v[70:71]
	v_pk_mul_f32 v[64:65], v[184:185], v[64:65]
	v_pk_mul_f32 v[66:67], v[186:187], v[66:67]
	v_pk_mul_f32 v[60:61], v[188:189], v[60:61]
	v_pk_mul_f32 v[62:63], v[190:191], v[62:63]
	v_pk_mul_f32 v[56:57], v[192:193], v[56:57]
	v_pk_mul_f32 v[58:59], v[194:195], v[58:59]
	v_cvt_pk_bf16_f32 v246, v68, v69
	v_cvt_pk_bf16_f32 v247, v70, v71
	v_cvt_pk_bf16_f32 v248, v64, v65
	v_cvt_pk_bf16_f32 v249, v66, v67
	v_cvt_pk_bf16_f32 v250, v60, v61
	v_cvt_pk_bf16_f32 v251, v62, v63
	v_cvt_pk_bf16_f32 v208, v56, v57
	v_cvt_pk_bf16_f32 v209, v58, v59
	s_add_u32 s2, s2, 0x28000
	s_addc_u32 s3, s3, 0
	s_add_u32 s18, s18, 0x28000
	s_addc_u32 s19, s19, 0
	s_add_u32 s78, s78, 0x28000
	s_addc_u32 s79, s79, 0
	s_add_u32 s22, s22, 0x28000
	s_addc_u32 s23, s23, 0
	s_mov_b64 vcc, s[6:7]
	v_cndmask_b32_dpp v68, v4, v0, vcc row_ror:8 row_mask:0xf bank_mask:0xf
	v_cndmask_b32_dpp v69, v5, v1, vcc row_ror:8 row_mask:0xf bank_mask:0xf
	v_cndmask_b32_dpp v70, v6, v2, vcc row_ror:8 row_mask:0xf bank_mask:0xf
	v_cndmask_b32_dpp v71, v7, v3, vcc row_ror:8 row_mask:0xf bank_mask:0xf
	v_cndmask_b32_dpp v60, v250, v246, vcc row_ror:8 row_mask:0xf bank_mask:0xf
	v_cndmask_b32_dpp v61, v251, v247, vcc row_ror:8 row_mask:0xf bank_mask:0xf
	v_cndmask_b32_dpp v62, v208, v248, vcc row_ror:8 row_mask:0xf bank_mask:0xf
	v_cndmask_b32_dpp v63, v209, v249, vcc row_ror:8 row_mask:0xf bank_mask:0xf
	s_not_b64 vcc, s[6:7]
	v_cndmask_b32_dpp v64, v0, v4, vcc row_ror:8 row_mask:0xf bank_mask:0xf
	v_cndmask_b32_dpp v65, v1, v5, vcc row_ror:8 row_mask:0xf bank_mask:0xf
	v_cndmask_b32_dpp v66, v2, v6, vcc row_ror:8 row_mask:0xf bank_mask:0xf
	v_cndmask_b32_dpp v67, v3, v7, vcc row_ror:8 row_mask:0xf bank_mask:0xf
	v_cndmask_b32_dpp v56, v246, v250, vcc row_ror:8 row_mask:0xf bank_mask:0xf
	v_cndmask_b32_dpp v57, v247, v251, vcc row_ror:8 row_mask:0xf bank_mask:0xf
	v_cndmask_b32_dpp v58, v248, v208, vcc row_ror:8 row_mask:0xf bank_mask:0xf
	v_cndmask_b32_dpp v59, v249, v209, vcc row_ror:8 row_mask:0xf bank_mask:0xf
	global_store_dwordx4 v171, v[68:71], s[2:3] nt
	global_store_dwordx4 v171, v[64:67], s[18:19] nt
	global_store_dwordx4 v171, v[60:63], s[78:79]
	global_store_dwordx4 v171, v[56:59], s[22:23]
	s_waitcnt vmcnt(16)
	s_mov_b64 vcc, s[6:7]
	v_cndmask_b32_dpp v0, v242, v238, vcc row_ror:8 row_mask:0xf bank_mask:0xf
	v_cndmask_b32_dpp v1, v243, v239, vcc row_ror:8 row_mask:0xf bank_mask:0xf
	v_cndmask_b32_dpp v2, v244, v240, vcc row_ror:8 row_mask:0xf bank_mask:0xf
	v_cndmask_b32_dpp v3, v245, v241, vcc row_ror:8 row_mask:0xf bank_mask:0xf
	s_not_b64 vcc, s[6:7]
	v_cndmask_b32_dpp v4, v238, v242, vcc row_ror:8 row_mask:0xf bank_mask:0xf
	v_cndmask_b32_dpp v5, v239, v243, vcc row_ror:8 row_mask:0xf bank_mask:0xf
	v_cndmask_b32_dpp v6, v240, v244, vcc row_ror:8 row_mask:0xf bank_mask:0xf
	v_cndmask_b32_dpp v7, v241, v245, vcc row_ror:8 row_mask:0xf bank_mask:0xf
	v_lshlrev_b32_e32 v246, 16, v0
	v_and_b32_e32 v247, 0xffff0000, v0
	v_pk_fma_f32 v[52:53], v[52:53], v[142:143], v[246:247]
	v_lshlrev_b32_e32 v248, 16, v1
	v_and_b32_e32 v249, 0xffff0000, v1
	v_pk_fma_f32 v[54:55], v[54:55], v[144:145], v[248:249]
	v_lshlrev_b32_e32 v250, 16, v2
	v_and_b32_e32 v251, 0xffff0000, v2
	v_pk_fma_f32 v[48:49], v[48:49], v[150:151], v[250:251]
	v_lshlrev_b32_e32 v208, 16, v3
	v_and_b32_e32 v209, 0xffff0000, v3
	v_pk_fma_f32 v[50:51], v[50:51], v[152:153], v[208:209]
	v_lshlrev_b32_e32 v246, 16, v4
	v_and_b32_e32 v247, 0xffff0000, v4
	v_pk_fma_f32 v[44:45], v[44:45], v[138:139], v[246:247]
	v_lshlrev_b32_e32 v248, 16, v5
	v_and_b32_e32 v249, 0xffff0000, v5
	v_pk_fma_f32 v[46:47], v[46:47], v[140:141], v[248:249]
	v_lshlrev_b32_e32 v250, 16, v6
	v_and_b32_e32 v251, 0xffff0000, v6
	v_pk_fma_f32 v[40:41], v[40:41], v[146:147], v[250:251]
	v_lshlrev_b32_e32 v208, 16, v7
	v_and_b32_e32 v209, 0xffff0000, v7
	v_pk_fma_f32 v[42:43], v[42:43], v[148:149], v[208:209]
	v_cvt_pk_bf16_f32 v0, v52, v53
	v_cvt_pk_bf16_f32 v1, v54, v55
	v_cvt_pk_bf16_f32 v2, v48, v49
	v_cvt_pk_bf16_f32 v3, v50, v51
	v_cvt_pk_bf16_f32 v4, v44, v45
	v_cvt_pk_bf16_f32 v5, v46, v47
	v_cvt_pk_bf16_f32 v6, v40, v41
	v_cvt_pk_bf16_f32 v7, v42, v43
	v_mul_f32_e32 v246, v53, v53
	v_mul_f32_e32 v248, v55, v55
	v_fmac_f32_e32 v246, v52, v52
	v_fmac_f32_e32 v248, v54, v54
	v_add_f32_e32 v246, v246, v248
	v_mul_f32_e32 v248, v49, v49
	v_fmac_f32_e32 v248, v48, v48
	v_add_f32_e32 v246, v246, v248
	v_mul_f32_e32 v248, v51, v51
	v_fmac_f32_e32 v248, v50, v50
	v_add_f32_e32 v246, v248, v246
	v_mul_f32_e32 v247, v45, v45
	v_mul_f32_e32 v248, v47, v47
	v_fmac_f32_e32 v247, v44, v44
	v_fmac_f32_e32 v248, v46, v46
	v_add_f32_e32 v247, v247, v248
	v_mul_f32_e32 v248, v41, v41
	v_fmac_f32_e32 v248, v40, v40
	v_add_f32_e32 v247, v247, v248
	v_mul_f32_e32 v248, v43, v43
	v_fmac_f32_e32 v248, v42, v42
	v_add_f32_e32 v247, v248, v247
	v_add_f32_e32 v246, v246, v247
	v_mov_b32_e32 v247, v246
	s_nop 1
	v_permlane16_swap_b32_e32 v246, v247
	s_nop 1
	v_add_f32_e32 v246, v246, v247
	v_mov_b32_e32 v247, v246
	s_nop 1
	v_permlane32_swap_b32_e32 v246, v247
	v_add_u32_e32 v248, s8, v223
	s_nop 0
	v_add_f32_e32 v246, v246, v247
	s_mov_b64 exec, s[44:45]
	ds_write_b32 v248, v246 offset:2304
	s_mov_b64 exec, -1
	v_pk_mul_f32 v[52:53], v[180:181], v[52:53]
	v_pk_mul_f32 v[54:55], v[182:183], v[54:55]
	v_pk_mul_f32 v[48:49], v[184:185], v[48:49]
	v_pk_mul_f32 v[50:51], v[186:187], v[50:51]
	v_pk_mul_f32 v[44:45], v[188:189], v[44:45]
	v_pk_mul_f32 v[46:47], v[190:191], v[46:47]
	v_pk_mul_f32 v[40:41], v[192:193], v[40:41]
	v_pk_mul_f32 v[42:43], v[194:195], v[42:43]
	v_cvt_pk_bf16_f32 v246, v52, v53
	v_cvt_pk_bf16_f32 v247, v54, v55
	v_cvt_pk_bf16_f32 v248, v48, v49
	v_cvt_pk_bf16_f32 v249, v50, v51
	v_cvt_pk_bf16_f32 v250, v44, v45
	v_cvt_pk_bf16_f32 v251, v46, v47
	v_cvt_pk_bf16_f32 v208, v40, v41
	v_cvt_pk_bf16_f32 v209, v42, v43
	s_add_u32 s2, s2, 0x8000
	s_addc_u32 s3, s3, 0
	s_add_u32 s18, s18, 0x8000
	s_addc_u32 s19, s19, 0
	s_add_u32 s78, s78, 0x8000
	s_addc_u32 s79, s79, 0
	s_add_u32 s22, s22, 0x8000
	s_addc_u32 s23, s23, 0
	s_mov_b64 vcc, s[6:7]
	v_cndmask_b32_dpp v52, v4, v0, vcc row_ror:8 row_mask:0xf bank_mask:0xf
	v_cndmask_b32_dpp v53, v5, v1, vcc row_ror:8 row_mask:0xf bank_mask:0xf
	v_cndmask_b32_dpp v54, v6, v2, vcc row_ror:8 row_mask:0xf bank_mask:0xf
	v_cndmask_b32_dpp v55, v7, v3, vcc row_ror:8 row_mask:0xf bank_mask:0xf
	v_cndmask_b32_dpp v44, v250, v246, vcc row_ror:8 row_mask:0xf bank_mask:0xf
	v_cndmask_b32_dpp v45, v251, v247, vcc row_ror:8 row_mask:0xf bank_mask:0xf
	v_cndmask_b32_dpp v46, v208, v248, vcc row_ror:8 row_mask:0xf bank_mask:0xf
	v_cndmask_b32_dpp v47, v209, v249, vcc row_ror:8 row_mask:0xf bank_mask:0xf
	s_not_b64 vcc, s[6:7]
	v_cndmask_b32_dpp v48, v0, v4, vcc row_ror:8 row_mask:0xf bank_mask:0xf
	v_cndmask_b32_dpp v49, v1, v5, vcc row_ror:8 row_mask:0xf bank_mask:0xf
	v_cndmask_b32_dpp v50, v2, v6, vcc row_ror:8 row_mask:0xf bank_mask:0xf
	v_cndmask_b32_dpp v51, v3, v7, vcc row_ror:8 row_mask:0xf bank_mask:0xf
	v_cndmask_b32_dpp v40, v246, v250, vcc row_ror:8 row_mask:0xf bank_mask:0xf
	v_cndmask_b32_dpp v41, v247, v251, vcc row_ror:8 row_mask:0xf bank_mask:0xf
	v_cndmask_b32_dpp v42, v248, v208, vcc row_ror:8 row_mask:0xf bank_mask:0xf
	v_cndmask_b32_dpp v43, v249, v209, vcc row_ror:8 row_mask:0xf bank_mask:0xf
	global_store_dwordx4 v171, v[52:55], s[2:3] nt
	global_store_dwordx4 v171, v[48:51], s[18:19] nt
	global_store_dwordx4 v171, v[44:47], s[78:79]
	global_store_dwordx4 v171, v[40:43], s[22:23]
	s_waitcnt vmcnt(14)
	s_mov_b64 vcc, s[6:7]
	v_cndmask_b32_dpp v0, v200, v196, vcc row_ror:8 row_mask:0xf bank_mask:0xf
	v_cndmask_b32_dpp v1, v201, v197, vcc row_ror:8 row_mask:0xf bank_mask:0xf
	v_cndmask_b32_dpp v2, v202, v198, vcc row_ror:8 row_mask:0xf bank_mask:0xf
	v_cndmask_b32_dpp v3, v203, v199, vcc row_ror:8 row_mask:0xf bank_mask:0xf
	s_not_b64 vcc, s[6:7]
	v_cndmask_b32_dpp v4, v196, v200, vcc row_ror:8 row_mask:0xf bank_mask:0xf
	v_cndmask_b32_dpp v5, v197, v201, vcc row_ror:8 row_mask:0xf bank_mask:0xf
	v_cndmask_b32_dpp v6, v198, v202, vcc row_ror:8 row_mask:0xf bank_mask:0xf
	v_cndmask_b32_dpp v7, v199, v203, vcc row_ror:8 row_mask:0xf bank_mask:0xf
	v_lshlrev_b32_e32 v246, 16, v0
	v_and_b32_e32 v247, 0xffff0000, v0
	v_pk_fma_f32 v[36:37], v[36:37], v[142:143], v[246:247]
	v_lshlrev_b32_e32 v248, 16, v1
	v_and_b32_e32 v249, 0xffff0000, v1
	v_pk_fma_f32 v[38:39], v[38:39], v[144:145], v[248:249]
	v_lshlrev_b32_e32 v250, 16, v2
	v_and_b32_e32 v251, 0xffff0000, v2
	v_pk_fma_f32 v[32:33], v[32:33], v[150:151], v[250:251]
	v_lshlrev_b32_e32 v208, 16, v3
	v_and_b32_e32 v209, 0xffff0000, v3
	v_pk_fma_f32 v[34:35], v[34:35], v[152:153], v[208:209]
	v_lshlrev_b32_e32 v246, 16, v4
	v_and_b32_e32 v247, 0xffff0000, v4
	v_pk_fma_f32 v[28:29], v[28:29], v[138:139], v[246:247]
	v_lshlrev_b32_e32 v248, 16, v5
	v_and_b32_e32 v249, 0xffff0000, v5
	v_pk_fma_f32 v[30:31], v[30:31], v[140:141], v[248:249]
	v_lshlrev_b32_e32 v250, 16, v6
	v_and_b32_e32 v251, 0xffff0000, v6
	v_pk_fma_f32 v[24:25], v[24:25], v[146:147], v[250:251]
	v_lshlrev_b32_e32 v208, 16, v7
	v_and_b32_e32 v209, 0xffff0000, v7
	v_pk_fma_f32 v[26:27], v[26:27], v[148:149], v[208:209]
	v_cvt_pk_bf16_f32 v0, v36, v37
	v_cvt_pk_bf16_f32 v1, v38, v39
	v_cvt_pk_bf16_f32 v2, v32, v33
	v_cvt_pk_bf16_f32 v3, v34, v35
	v_cvt_pk_bf16_f32 v4, v28, v29
	v_cvt_pk_bf16_f32 v5, v30, v31
	v_cvt_pk_bf16_f32 v6, v24, v25
	v_cvt_pk_bf16_f32 v7, v26, v27
	v_mul_f32_e32 v246, v37, v37
	v_mul_f32_e32 v248, v39, v39
	v_fmac_f32_e32 v246, v36, v36
	v_fmac_f32_e32 v248, v38, v38
	v_add_f32_e32 v246, v246, v248
	v_mul_f32_e32 v248, v33, v33
	v_fmac_f32_e32 v248, v32, v32
	v_add_f32_e32 v246, v246, v248
	v_mul_f32_e32 v248, v35, v35
	v_fmac_f32_e32 v248, v34, v34
	v_add_f32_e32 v246, v248, v246
	v_mul_f32_e32 v247, v29, v29
	v_mul_f32_e32 v248, v31, v31
	v_fmac_f32_e32 v247, v28, v28
	v_fmac_f32_e32 v248, v30, v30
	v_add_f32_e32 v247, v247, v248
	v_mul_f32_e32 v248, v25, v25
	v_fmac_f32_e32 v248, v24, v24
	v_add_f32_e32 v247, v247, v248
	v_mul_f32_e32 v248, v27, v27
	v_fmac_f32_e32 v248, v26, v26
	v_add_f32_e32 v247, v248, v247
	v_add_f32_e32 v246, v246, v247
	v_mov_b32_e32 v247, v246
	s_nop 1
	v_permlane16_swap_b32_e32 v246, v247
	s_nop 1
	v_add_f32_e32 v246, v246, v247
	v_mov_b32_e32 v247, v246
	s_nop 1
	v_permlane32_swap_b32_e32 v246, v247
	v_add_u32_e32 v248, s8, v223
	s_nop 0
	v_add_f32_e32 v246, v246, v247
	s_mov_b64 exec, s[44:45]
	ds_write_b32 v248, v246 offset:2560
	s_mov_b64 exec, -1
	v_pk_mul_f32 v[36:37], v[180:181], v[36:37]
	v_pk_mul_f32 v[38:39], v[182:183], v[38:39]
	v_pk_mul_f32 v[32:33], v[184:185], v[32:33]
	v_pk_mul_f32 v[34:35], v[186:187], v[34:35]
	v_pk_mul_f32 v[28:29], v[188:189], v[28:29]
	v_pk_mul_f32 v[30:31], v[190:191], v[30:31]
	v_pk_mul_f32 v[24:25], v[192:193], v[24:25]
	v_pk_mul_f32 v[26:27], v[194:195], v[26:27]
	v_cvt_pk_bf16_f32 v246, v36, v37
	v_cvt_pk_bf16_f32 v247, v38, v39
	v_cvt_pk_bf16_f32 v248, v32, v33
	v_cvt_pk_bf16_f32 v249, v34, v35
	v_cvt_pk_bf16_f32 v250, v28, v29
	v_cvt_pk_bf16_f32 v251, v30, v31
	v_cvt_pk_bf16_f32 v208, v24, v25
	v_cvt_pk_bf16_f32 v209, v26, v27
	s_add_u32 s2, s2, 0x8000
	s_addc_u32 s3, s3, 0
	s_add_u32 s18, s18, 0x8000
	s_addc_u32 s19, s19, 0
	s_add_u32 s78, s78, 0x8000
	s_addc_u32 s79, s79, 0
	s_add_u32 s22, s22, 0x8000
	s_addc_u32 s23, s23, 0
	s_mov_b64 vcc, s[6:7]
	v_cndmask_b32_dpp v36, v4, v0, vcc row_ror:8 row_mask:0xf bank_mask:0xf
	v_cndmask_b32_dpp v37, v5, v1, vcc row_ror:8 row_mask:0xf bank_mask:0xf
	v_cndmask_b32_dpp v38, v6, v2, vcc row_ror:8 row_mask:0xf bank_mask:0xf
	v_cndmask_b32_dpp v39, v7, v3, vcc row_ror:8 row_mask:0xf bank_mask:0xf
	v_cndmask_b32_dpp v28, v250, v246, vcc row_ror:8 row_mask:0xf bank_mask:0xf
	v_cndmask_b32_dpp v29, v251, v247, vcc row_ror:8 row_mask:0xf bank_mask:0xf
	v_cndmask_b32_dpp v30, v208, v248, vcc row_ror:8 row_mask:0xf bank_mask:0xf
	v_cndmask_b32_dpp v31, v209, v249, vcc row_ror:8 row_mask:0xf bank_mask:0xf
	s_not_b64 vcc, s[6:7]
	v_cndmask_b32_dpp v32, v0, v4, vcc row_ror:8 row_mask:0xf bank_mask:0xf
	v_cndmask_b32_dpp v33, v1, v5, vcc row_ror:8 row_mask:0xf bank_mask:0xf
	v_cndmask_b32_dpp v34, v2, v6, vcc row_ror:8 row_mask:0xf bank_mask:0xf
	v_cndmask_b32_dpp v35, v3, v7, vcc row_ror:8 row_mask:0xf bank_mask:0xf
	v_cndmask_b32_dpp v24, v246, v250, vcc row_ror:8 row_mask:0xf bank_mask:0xf
	v_cndmask_b32_dpp v25, v247, v251, vcc row_ror:8 row_mask:0xf bank_mask:0xf
	v_cndmask_b32_dpp v26, v248, v208, vcc row_ror:8 row_mask:0xf bank_mask:0xf
	v_cndmask_b32_dpp v27, v249, v209, vcc row_ror:8 row_mask:0xf bank_mask:0xf
	global_store_dwordx4 v171, v[36:39], s[2:3] nt
	global_store_dwordx4 v171, v[32:35], s[18:19] nt
	global_store_dwordx4 v171, v[28:31], s[78:79]
	global_store_dwordx4 v171, v[24:27], s[22:23]
	s_waitcnt vmcnt(12)
	s_mov_b64 vcc, s[6:7]
	v_cndmask_b32_dpp v0, v234, v204, vcc row_ror:8 row_mask:0xf bank_mask:0xf
	v_cndmask_b32_dpp v1, v235, v205, vcc row_ror:8 row_mask:0xf bank_mask:0xf
	v_cndmask_b32_dpp v2, v236, v206, vcc row_ror:8 row_mask:0xf bank_mask:0xf
	v_cndmask_b32_dpp v3, v237, v207, vcc row_ror:8 row_mask:0xf bank_mask:0xf
	s_not_b64 vcc, s[6:7]
	v_cndmask_b32_dpp v4, v204, v234, vcc row_ror:8 row_mask:0xf bank_mask:0xf
	v_cndmask_b32_dpp v5, v205, v235, vcc row_ror:8 row_mask:0xf bank_mask:0xf
	v_cndmask_b32_dpp v6, v206, v236, vcc row_ror:8 row_mask:0xf bank_mask:0xf
	v_cndmask_b32_dpp v7, v207, v237, vcc row_ror:8 row_mask:0xf bank_mask:0xf
	v_lshlrev_b32_e32 v246, 16, v0
	v_and_b32_e32 v247, 0xffff0000, v0
	v_pk_fma_f32 v[20:21], v[20:21], v[142:143], v[246:247]
	v_lshlrev_b32_e32 v248, 16, v1
	v_and_b32_e32 v249, 0xffff0000, v1
	v_pk_fma_f32 v[22:23], v[22:23], v[144:145], v[248:249]
	v_lshlrev_b32_e32 v250, 16, v2
	v_and_b32_e32 v251, 0xffff0000, v2
	v_pk_fma_f32 v[16:17], v[16:17], v[150:151], v[250:251]
	v_lshlrev_b32_e32 v208, 16, v3
	v_and_b32_e32 v209, 0xffff0000, v3
	v_pk_fma_f32 v[18:19], v[18:19], v[152:153], v[208:209]
	v_lshlrev_b32_e32 v246, 16, v4
	v_and_b32_e32 v247, 0xffff0000, v4
	v_pk_fma_f32 v[12:13], v[12:13], v[138:139], v[246:247]
	v_lshlrev_b32_e32 v248, 16, v5
	v_and_b32_e32 v249, 0xffff0000, v5
	v_pk_fma_f32 v[14:15], v[14:15], v[140:141], v[248:249]
	v_lshlrev_b32_e32 v250, 16, v6
	v_and_b32_e32 v251, 0xffff0000, v6
	v_pk_fma_f32 v[8:9], v[8:9], v[146:147], v[250:251]
	v_lshlrev_b32_e32 v208, 16, v7
	v_and_b32_e32 v209, 0xffff0000, v7
	v_pk_fma_f32 v[10:11], v[10:11], v[148:149], v[208:209]
	v_cvt_pk_bf16_f32 v0, v20, v21
	v_cvt_pk_bf16_f32 v1, v22, v23
	v_cvt_pk_bf16_f32 v2, v16, v17
	v_cvt_pk_bf16_f32 v3, v18, v19
	v_cvt_pk_bf16_f32 v4, v12, v13
	v_cvt_pk_bf16_f32 v5, v14, v15
	v_cvt_pk_bf16_f32 v6, v8, v9
	v_cvt_pk_bf16_f32 v7, v10, v11
	v_mul_f32_e32 v246, v21, v21
	v_mul_f32_e32 v248, v23, v23
	v_fmac_f32_e32 v246, v20, v20
	v_fmac_f32_e32 v248, v22, v22
	v_add_f32_e32 v246, v246, v248
	v_mul_f32_e32 v248, v17, v17
	v_fmac_f32_e32 v248, v16, v16
	v_add_f32_e32 v246, v246, v248
	v_mul_f32_e32 v248, v19, v19
	v_fmac_f32_e32 v248, v18, v18
	v_add_f32_e32 v246, v248, v246
	v_mul_f32_e32 v247, v13, v13
	v_mul_f32_e32 v248, v15, v15
	v_fmac_f32_e32 v247, v12, v12
	v_fmac_f32_e32 v248, v14, v14
	v_add_f32_e32 v247, v247, v248
	v_mul_f32_e32 v248, v9, v9
	v_fmac_f32_e32 v248, v8, v8
	v_add_f32_e32 v247, v247, v248
	v_mul_f32_e32 v248, v11, v11
	v_fmac_f32_e32 v248, v10, v10
	v_add_f32_e32 v247, v248, v247
	v_add_f32_e32 v246, v246, v247
	v_mov_b32_e32 v247, v246
	s_nop 1
	v_permlane16_swap_b32_e32 v246, v247
	s_nop 1
	v_add_f32_e32 v246, v246, v247
	v_mov_b32_e32 v247, v246
	s_nop 1
	v_permlane32_swap_b32_e32 v246, v247
	v_add_u32_e32 v248, s8, v223
	s_nop 0
	v_add_f32_e32 v246, v246, v247
	s_mov_b64 exec, s[44:45]
	ds_write_b32 v248, v246 offset:2816
	s_mov_b64 exec, -1
	v_pk_mul_f32 v[20:21], v[180:181], v[20:21]
	v_pk_mul_f32 v[22:23], v[182:183], v[22:23]
	v_pk_mul_f32 v[16:17], v[184:185], v[16:17]
	v_pk_mul_f32 v[18:19], v[186:187], v[18:19]
	v_pk_mul_f32 v[12:13], v[188:189], v[12:13]
	v_pk_mul_f32 v[14:15], v[190:191], v[14:15]
	v_pk_mul_f32 v[8:9], v[192:193], v[8:9]
	v_pk_mul_f32 v[10:11], v[194:195], v[10:11]
	v_cvt_pk_bf16_f32 v246, v20, v21
	v_cvt_pk_bf16_f32 v247, v22, v23
	v_cvt_pk_bf16_f32 v248, v16, v17
	v_cvt_pk_bf16_f32 v249, v18, v19
	v_cvt_pk_bf16_f32 v250, v12, v13
	v_cvt_pk_bf16_f32 v251, v14, v15
	v_cvt_pk_bf16_f32 v208, v8, v9
	v_cvt_pk_bf16_f32 v209, v10, v11
	s_add_u32 s2, s2, 0x8000
	s_addc_u32 s3, s3, 0
	s_add_u32 s18, s18, 0x8000
	s_addc_u32 s19, s19, 0
	s_add_u32 s78, s78, 0x8000
	s_addc_u32 s79, s79, 0
	s_add_u32 s22, s22, 0x8000
	s_addc_u32 s23, s23, 0
	s_mov_b64 vcc, s[6:7]
	v_cndmask_b32_dpp v20, v4, v0, vcc row_ror:8 row_mask:0xf bank_mask:0xf
	v_cndmask_b32_dpp v21, v5, v1, vcc row_ror:8 row_mask:0xf bank_mask:0xf
	v_cndmask_b32_dpp v22, v6, v2, vcc row_ror:8 row_mask:0xf bank_mask:0xf
	v_cndmask_b32_dpp v23, v7, v3, vcc row_ror:8 row_mask:0xf bank_mask:0xf
	v_cndmask_b32_dpp v12, v250, v246, vcc row_ror:8 row_mask:0xf bank_mask:0xf
	v_cndmask_b32_dpp v13, v251, v247, vcc row_ror:8 row_mask:0xf bank_mask:0xf
	v_cndmask_b32_dpp v14, v208, v248, vcc row_ror:8 row_mask:0xf bank_mask:0xf
	v_cndmask_b32_dpp v15, v209, v249, vcc row_ror:8 row_mask:0xf bank_mask:0xf
	s_not_b64 vcc, s[6:7]
	v_cndmask_b32_dpp v16, v0, v4, vcc row_ror:8 row_mask:0xf bank_mask:0xf
	v_cndmask_b32_dpp v17, v1, v5, vcc row_ror:8 row_mask:0xf bank_mask:0xf
	v_cndmask_b32_dpp v18, v2, v6, vcc row_ror:8 row_mask:0xf bank_mask:0xf
	v_cndmask_b32_dpp v19, v3, v7, vcc row_ror:8 row_mask:0xf bank_mask:0xf
	v_cndmask_b32_dpp v8, v246, v250, vcc row_ror:8 row_mask:0xf bank_mask:0xf
	v_cndmask_b32_dpp v9, v247, v251, vcc row_ror:8 row_mask:0xf bank_mask:0xf
	v_cndmask_b32_dpp v10, v248, v208, vcc row_ror:8 row_mask:0xf bank_mask:0xf
	v_cndmask_b32_dpp v11, v249, v209, vcc row_ror:8 row_mask:0xf bank_mask:0xf
	global_store_dwordx4 v171, v[20:23], s[2:3] nt
	global_store_dwordx4 v171, v[16:19], s[18:19] nt
	global_store_dwordx4 v171, v[12:15], s[78:79]
	global_store_dwordx4 v171, v[8:11], s[22:23]
	s_mov_b32 s100, 1
	s_branch .LBB0_714

.Lfo_first:
	s_lshr_b32 s14, s34, 3
	s_mul_i32 s14, s14, 0x3000
	s_add_u32 s16, s86, s14
	s_addc_u32 s17, s87, 0
	s_add_u32 s16, s16, 0x2000
	s_addc_u32 s17, s17, 0
	s_add_u32 s86, s88, s14
	s_addc_u32 s87, s89, 0
	s_add_u32 s86, s86, 0x1000
	s_addc_u32 s87, s87, 0
	v_lshl_add_u32 v171, v170, 1, v96
	v_lshl_add_u32 v171, v222, 11, v171
	v_lshlrev_b32_e32 v170, 2, v170
	s_lshl_b32 s14, s34, 8
	s_add_i32 s14, s14, s81
	s_mov_b64 s[12:13], s[18:19]
	s_lshl_b32 s31, s14, 12
	s_lshl_b32 s14, s14, 11
	s_add_u32 s2, s2, s14
	s_addc_u32 s3, s3, 0
	s_add_u32 s78, s78, s14
	s_addc_u32 s79, s79, 0
	s_add_u32 s22, s78, 0x4000
	s_addc_u32 s23, s79, 0
	s_add_u32 s18, s2, 0x4000
	s_addc_u32 s19, s3, 0
	s_add_u32 s14, s12, s31
	s_addc_u32 s15, s13, 0
	global_load_dwordx4 v[142:145], v170, s[16:17]
	global_load_dwordx4 v[150:153], v170, s[16:17] offset:16
	global_load_dwordx4 v[138:141], v170, s[16:17] offset:128
	global_load_dwordx4 v[146:149], v170, s[16:17] offset:144
	v_lshl_add_u32 v96, v163, 12, v170
	global_load_dwordx4 v[196:199], v96, s[14:15]
	global_load_dwordx4 v[200:203], v96, s[14:15] offset:16
	global_load_dwordx4 v[204:207], v96, s[14:15] offset:128
	global_load_dwordx4 v[234:237], v96, s[14:15] offset:144
	global_load_dwordx4 v[180:183], v170, s[86:87]
	global_load_dwordx4 v[184:187], v170, s[86:87] offset:16
	global_load_dwordx4 v[188:191], v170, s[86:87] offset:128
	global_load_dwordx4 v[192:195], v170, s[86:87] offset:144
	global_load_dwordx4 v[238:241], v170, s[26:27]
	global_load_dwordx4 v[242:245], v170, s[26:27] offset:16
	global_load_dwordx4 v[246:249], v170, s[26:27] offset:128
	global_load_dwordx4 v[4:7], v170, s[26:27] offset:144
	s_waitcnt vmcnt(0)
	v_pk_add_f32 v[182:183], v[182:183], 1.0 op_sel_hi:[1,0]
	v_pk_add_f32 v[180:181], v[180:181], 1.0 op_sel_hi:[1,0]
	v_pk_add_f32 v[186:187], v[186:187], 1.0 op_sel_hi:[1,0]
	v_pk_add_f32 v[184:185], v[184:185], 1.0 op_sel_hi:[1,0]
	v_pk_add_f32 v[190:191], v[190:191], 1.0 op_sel_hi:[1,0]
	v_pk_add_f32 v[188:189], v[188:189], 1.0 op_sel_hi:[1,0]
	v_pk_add_f32 v[194:195], v[194:195], 1.0 op_sel_hi:[1,0]
	v_pk_add_f32 v[192:193], v[192:193], 1.0 op_sel_hi:[1,0]
	v_pk_mul_f32 v[182:183], v[240:241], v[182:183]
	v_pk_mul_f32 v[180:181], v[238:239], v[180:181]
	v_pk_mul_f32 v[186:187], v[244:245], v[186:187]
	v_pk_mul_f32 v[184:185], v[242:243], v[184:185]
	v_pk_mul_f32 v[190:191], v[248:249], v[190:191]
	v_pk_mul_f32 v[188:189], v[246:247], v[188:189]
	v_pk_mul_f32 v[194:195], v[6:7], v[194:195]
	v_pk_mul_f32 v[192:193], v[4:5], v[192:193]
	s_add_u32 s14, s14, 0x10000
	s_addc_u32 s15, s15, 0
	global_load_dwordx4 v[238:241], v96, s[14:15]
	global_load_dwordx4 v[242:245], v96, s[14:15] offset:16
	v_pk_fma_f32 v[134:135], v[134:135], v[142:143], v[196:197]
	v_pk_fma_f32 v[136:137], v[136:137], v[144:145], v[198:199]
	v_pk_fma_f32 v[130:131], v[130:131], v[150:151], v[200:201]
	v_pk_fma_f32 v[132:133], v[132:133], v[152:153], v[202:203]
	v_pk_fma_f32 v[126:127], v[126:127], v[138:139], v[204:205]
	v_pk_fma_f32 v[128:129], v[128:129], v[140:141], v[206:207]
	v_pk_fma_f32 v[122:123], v[122:123], v[146:147], v[234:235]
	v_pk_fma_f32 v[124:125], v[124:125], v[148:149], v[236:237]
	global_load_dwordx4 v[196:199], v96, s[14:15] offset:128
	global_load_dwordx4 v[200:203], v96, s[14:15] offset:144
	s_add_u32 s14, s14, 0x10000
	s_addc_u32 s15, s15, 0
	global_load_dwordx4 v[204:207], v96, s[14:15]
	global_load_dwordx4 v[234:237], v96, s[14:15] offset:16
	v_cvt_pk_bf16_f32 v0, v134, v135
	v_cvt_pk_bf16_f32 v1, v136, v137
	v_cvt_pk_bf16_f32 v2, v130, v131
	v_cvt_pk_bf16_f32 v3, v132, v133
	v_cvt_pk_bf16_f32 v4, v126, v127
	v_cvt_pk_bf16_f32 v5, v128, v129
	v_cvt_pk_bf16_f32 v6, v122, v123
	v_cvt_pk_bf16_f32 v7, v124, v125
	v_mul_f32_e32 v246, v135, v135
	v_mul_f32_e32 v248, v137, v137
	v_fmac_f32_e32 v246, v134, v134
	v_fmac_f32_e32 v248, v136, v136
	v_add_f32_e32 v246, v246, v248
	v_mul_f32_e32 v248, v131, v131
	v_fmac_f32_e32 v248, v130, v130
	v_add_f32_e32 v246, v246, v248
	v_mul_f32_e32 v248, v133, v133
	v_fmac_f32_e32 v248, v132, v132
	v_add_f32_e32 v246, v248, v246
	v_mul_f32_e32 v247, v127, v127
	v_mul_f32_e32 v248, v129, v129
	v_fmac_f32_e32 v247, v126, v126
	v_fmac_f32_e32 v248, v128, v128
	v_add_f32_e32 v247, v247, v248
	v_mul_f32_e32 v248, v123, v123
	v_fmac_f32_e32 v248, v122, v122
	v_add_f32_e32 v247, v247, v248
	v_mul_f32_e32 v248, v125, v125
	v_fmac_f32_e32 v248, v124, v124
	v_add_f32_e32 v247, v248, v247
	v_add_f32_e32 v246, v246, v247
	v_mov_b32_e32 v247, v246
	s_nop 1
	v_permlane16_swap_b32_e32 v246, v247
	s_nop 1
	v_add_f32_e32 v246, v246, v247
	v_mov_b32_e32 v247, v246
	s_nop 1
	v_permlane32_swap_b32_e32 v246, v247
	v_add_u32_e32 v248, s8, v223
	s_nop 0
	v_add_f32_e32 v246, v246, v247
	s_mov_b64 exec, s[44:45]
	ds_write_b32 v248, v246
	s_mov_b64 exec, -1
	v_pk_mul_f32 v[134:135], v[180:181], v[134:135]
	v_pk_mul_f32 v[136:137], v[182:183], v[136:137]
	v_pk_mul_f32 v[130:131], v[184:185], v[130:131]
	v_pk_mul_f32 v[132:133], v[186:187], v[132:133]
	v_pk_mul_f32 v[126:127], v[188:189], v[126:127]
	v_pk_mul_f32 v[128:129], v[190:191], v[128:129]
	v_pk_mul_f32 v[122:123], v[192:193], v[122:123]
	v_pk_mul_f32 v[124:125], v[194:195], v[124:125]
	v_cvt_pk_bf16_f32 v246, v134, v135
	v_cvt_pk_bf16_f32 v247, v136, v137
	v_cvt_pk_bf16_f32 v248, v130, v131
	v_cvt_pk_bf16_f32 v249, v132, v133
	v_cvt_pk_bf16_f32 v250, v126, v127
	v_cvt_pk_bf16_f32 v251, v128, v129
	v_cvt_pk_bf16_f32 v208, v122, v123
	v_cvt_pk_bf16_f32 v209, v124, v125
	s_nop 1
	s_mov_b64 vcc, s[6:7]
	v_cndmask_b32_dpp v134, v4, v0, vcc row_ror:8 row_mask:0xf bank_mask:0xf
	v_cndmask_b32_dpp v135, v5, v1, vcc row_ror:8 row_mask:0xf bank_mask:0xf
	v_cndmask_b32_dpp v136, v6, v2, vcc row_ror:8 row_mask:0xf bank_mask:0xf
	v_cndmask_b32_dpp v137, v7, v3, vcc row_ror:8 row_mask:0xf bank_mask:0xf
	v_cndmask_b32_dpp v126, v250, v246, vcc row_ror:8 row_mask:0xf bank_mask:0xf
	v_cndmask_b32_dpp v127, v251, v247, vcc row_ror:8 row_mask:0xf bank_mask:0xf
	v_cndmask_b32_dpp v128, v208, v248, vcc row_ror:8 row_mask:0xf bank_mask:0xf
	v_cndmask_b32_dpp v129, v209, v249, vcc row_ror:8 row_mask:0xf bank_mask:0xf
	s_not_b64 vcc, s[6:7]
	v_cndmask_b32_dpp v130, v0, v4, vcc row_ror:8 row_mask:0xf bank_mask:0xf
	v_cndmask_b32_dpp v131, v1, v5, vcc row_ror:8 row_mask:0xf bank_mask:0xf
	v_cndmask_b32_dpp v132, v2, v6, vcc row_ror:8 row_mask:0xf bank_mask:0xf
	v_cndmask_b32_dpp v133, v3, v7, vcc row_ror:8 row_mask:0xf bank_mask:0xf
	v_cndmask_b32_dpp v122, v246, v250, vcc row_ror:8 row_mask:0xf bank_mask:0xf
	v_cndmask_b32_dpp v123, v247, v251, vcc row_ror:8 row_mask:0xf bank_mask:0xf
	v_cndmask_b32_dpp v124, v248, v208, vcc row_ror:8 row_mask:0xf bank_mask:0xf
	v_cndmask_b32_dpp v125, v249, v209, vcc row_ror:8 row_mask:0xf bank_mask:0xf
	global_store_dwordx4 v171, v[134:137], s[2:3] nt
	global_store_dwordx4 v171, v[130:133], s[18:19] nt
	global_store_dwordx4 v171, v[126:129], s[78:79]
	global_store_dwordx4 v171, v[122:125], s[22:23]
	s_waitcnt vmcnt(6)
	v_pk_fma_f32 v[118:119], v[118:119], v[142:143], v[238:239]
	v_pk_fma_f32 v[120:121], v[120:121], v[144:145], v[240:241]
	v_pk_fma_f32 v[114:115], v[114:115], v[150:151], v[242:243]
	v_pk_fma_f32 v[116:117], v[116:117], v[152:153], v[244:245]
	v_pk_fma_f32 v[110:111], v[110:111], v[138:139], v[196:197]
	v_pk_fma_f32 v[112:113], v[112:113], v[140:141], v[198:199]
	v_pk_fma_f32 v[106:107], v[106:107], v[146:147], v[200:201]
	v_pk_fma_f32 v[108:109], v[108:109], v[148:149], v[202:203]
	global_load_dwordx4 v[238:241], v96, s[14:15] offset:128
	global_load_dwordx4 v[242:245], v96, s[14:15] offset:144
	s_add_u32 s14, s14, 0x10000
	s_addc_u32 s15, s15, 0
	global_load_dwordx4 v[196:199], v96, s[14:15]
	global_load_dwordx4 v[200:203], v96, s[14:15] offset:16
	v_cvt_pk_bf16_f32 v0, v118, v119
	v_cvt_pk_bf16_f32 v1, v120, v121
	v_cvt_pk_bf16_f32 v2, v114, v115
	v_cvt_pk_bf16_f32 v3, v116, v117
	v_cvt_pk_bf16_f32 v4, v110, v111
	v_cvt_pk_bf16_f32 v5, v112, v113
	v_cvt_pk_bf16_f32 v6, v106, v107
	v_cvt_pk_bf16_f32 v7, v108, v109
	v_mul_f32_e32 v246, v119, v119
	v_mul_f32_e32 v248, v121, v121
	v_fmac_f32_e32 v246, v118, v118
	v_fmac_f32_e32 v248, v120, v120
	v_add_f32_e32 v246, v246, v248
	v_mul_f32_e32 v248, v115, v115
	v_fmac_f32_e32 v248, v114, v114
	v_add_f32_e32 v246, v246, v248
	v_mul_f32_e32 v248, v117, v117
	v_fmac_f32_e32 v248, v116, v116
	v_add_f32_e32 v246, v248, v246
	v_mul_f32_e32 v247, v111, v111
	v_mul_f32_e32 v248, v113, v113
	v_fmac_f32_e32 v247, v110, v110
	v_fmac_f32_e32 v248, v112, v112
	v_add_f32_e32 v247, v247, v248
	v_mul_f32_e32 v248, v107, v107
	v_fmac_f32_e32 v248, v106, v106
	v_add_f32_e32 v247, v247, v248
	v_mul_f32_e32 v248, v109, v109
	v_fmac_f32_e32 v248, v108, v108
	v_add_f32_e32 v247, v248, v247
	v_add_f32_e32 v246, v246, v247
	v_mov_b32_e32 v247, v246
	s_nop 1
	v_permlane16_swap_b32_e32 v246, v247
	s_nop 1
	v_add_f32_e32 v246, v246, v247
	v_mov_b32_e32 v247, v246
	s_nop 1
	v_permlane32_swap_b32_e32 v246, v247
	v_add_u32_e32 v248, s8, v223
	s_nop 0
	v_add_f32_e32 v246, v246, v247
	s_mov_b64 exec, s[44:45]
	ds_write_b32 v248, v246 offset:256
	s_mov_b64 exec, -1
	v_pk_mul_f32 v[118:119], v[180:181], v[118:119]
	v_pk_mul_f32 v[120:121], v[182:183], v[120:121]
	v_pk_mul_f32 v[114:115], v[184:185], v[114:115]
	v_pk_mul_f32 v[116:117], v[186:187], v[116:117]
	v_pk_mul_f32 v[110:111], v[188:189], v[110:111]
	v_pk_mul_f32 v[112:113], v[190:191], v[112:113]
	v_pk_mul_f32 v[106:107], v[192:193], v[106:107]
	v_pk_mul_f32 v[108:109], v[194:195], v[108:109]
	v_cvt_pk_bf16_f32 v246, v118, v119
	v_cvt_pk_bf16_f32 v247, v120, v121
	v_cvt_pk_bf16_f32 v248, v114, v115
	v_cvt_pk_bf16_f32 v249, v116, v117
	v_cvt_pk_bf16_f32 v250, v110, v111
	v_cvt_pk_bf16_f32 v251, v112, v113
	v_cvt_pk_bf16_f32 v208, v106, v107
	v_cvt_pk_bf16_f32 v209, v108, v109
	s_add_u32 s2, s2, 0x8000
	s_addc_u32 s3, s3, 0
	s_add_u32 s18, s18, 0x8000
	s_addc_u32 s19, s19, 0
	s_add_u32 s78, s78, 0x8000
	s_addc_u32 s79, s79, 0
	s_add_u32 s22, s22, 0x8000
	s_addc_u32 s23, s23, 0
	s_mov_b64 vcc, s[6:7]
	v_cndmask_b32_dpp v118, v4, v0, vcc row_ror:8 row_mask:0xf bank_mask:0xf
	v_cndmask_b32_dpp v119, v5, v1, vcc row_ror:8 row_mask:0xf bank_mask:0xf
	v_cndmask_b32_dpp v120, v6, v2, vcc row_ror:8 row_mask:0xf bank_mask:0xf
	v_cndmask_b32_dpp v121, v7, v3, vcc row_ror:8 row_mask:0xf bank_mask:0xf
	v_cndmask_b32_dpp v110, v250, v246, vcc row_ror:8 row_mask:0xf bank_mask:0xf
	v_cndmask_b32_dpp v111, v251, v247, vcc row_ror:8 row_mask:0xf bank_mask:0xf
	v_cndmask_b32_dpp v112, v208, v248, vcc row_ror:8 row_mask:0xf bank_mask:0xf
	v_cndmask_b32_dpp v113, v209, v249, vcc row_ror:8 row_mask:0xf bank_mask:0xf
	s_not_b64 vcc, s[6:7]
	v_cndmask_b32_dpp v114, v0, v4, vcc row_ror:8 row_mask:0xf bank_mask:0xf
	v_cndmask_b32_dpp v115, v1, v5, vcc row_ror:8 row_mask:0xf bank_mask:0xf
	v_cndmask_b32_dpp v116, v2, v6, vcc row_ror:8 row_mask:0xf bank_mask:0xf
	v_cndmask_b32_dpp v117, v3, v7, vcc row_ror:8 row_mask:0xf bank_mask:0xf
	v_cndmask_b32_dpp v106, v246, v250, vcc row_ror:8 row_mask:0xf bank_mask:0xf
	v_cndmask_b32_dpp v107, v247, v251, vcc row_ror:8 row_mask:0xf bank_mask:0xf
	v_cndmask_b32_dpp v108, v248, v208, vcc row_ror:8 row_mask:0xf bank_mask:0xf
	v_cndmask_b32_dpp v109, v249, v209, vcc row_ror:8 row_mask:0xf bank_mask:0xf
	global_store_dwordx4 v171, v[118:121], s[2:3] nt
	global_store_dwordx4 v171, v[114:117], s[18:19] nt
	global_store_dwordx4 v171, v[110:113], s[78:79]
	global_store_dwordx4 v171, v[106:109], s[22:23]
	s_waitcnt vmcnt(6)
	v_pk_fma_f32 v[102:103], v[102:103], v[142:143], v[204:205]
	v_pk_fma_f32 v[104:105], v[104:105], v[144:145], v[206:207]
	v_pk_fma_f32 v[98:99], v[98:99], v[150:151], v[234:235]
	v_pk_fma_f32 v[100:101], v[100:101], v[152:153], v[236:237]
	v_pk_fma_f32 v[92:93], v[92:93], v[138:139], v[238:239]
	v_pk_fma_f32 v[94:95], v[94:95], v[140:141], v[240:241]
	v_pk_fma_f32 v[88:89], v[88:89], v[146:147], v[242:243]
	v_pk_fma_f32 v[90:91], v[90:91], v[148:149], v[244:245]
	global_load_dwordx4 v[204:207], v96, s[14:15] offset:128
	global_load_dwordx4 v[234:237], v96, s[14:15] offset:144
	s_add_u32 s14, s14, 0x50000
	s_addc_u32 s15, s15, 0
	global_load_dwordx4 v[238:241], v96, s[14:15]
	global_load_dwordx4 v[242:245], v96, s[14:15] offset:16
	v_cvt_pk_bf16_f32 v0, v102, v103
	v_cvt_pk_bf16_f32 v1, v104, v105
	v_cvt_pk_bf16_f32 v2, v98, v99
	v_cvt_pk_bf16_f32 v3, v100, v101
	v_cvt_pk_bf16_f32 v4, v92, v93
	v_cvt_pk_bf16_f32 v5, v94, v95
	v_cvt_pk_bf16_f32 v6, v88, v89
	v_cvt_pk_bf16_f32 v7, v90, v91
	v_mul_f32_e32 v246, v103, v103
	v_mul_f32_e32 v248, v105, v105
	v_fmac_f32_e32 v246, v102, v102
	v_fmac_f32_e32 v248, v104, v104
	v_add_f32_e32 v246, v246, v248
	v_mul_f32_e32 v248, v99, v99
	v_fmac_f32_e32 v248, v98, v98
	v_add_f32_e32 v246, v246, v248
	v_mul_f32_e32 v248, v101, v101
	v_fmac_f32_e32 v248, v100, v100
	v_add_f32_e32 v246, v248, v246
	v_mul_f32_e32 v247, v93, v93
	v_mul_f32_e32 v248, v95, v95
	v_fmac_f32_e32 v247, v92, v92
	v_fmac_f32_e32 v248, v94, v94
	v_add_f32_e32 v247, v247, v248
	v_mul_f32_e32 v248, v89, v89
	v_fmac_f32_e32 v248, v88, v88
	v_add_f32_e32 v247, v247, v248
	v_mul_f32_e32 v248, v91, v91
	v_fmac_f32_e32 v248, v90, v90
	v_add_f32_e32 v247, v248, v247
	v_add_f32_e32 v246, v246, v247
	v_mov_b32_e32 v247, v246
	s_nop 1
	v_permlane16_swap_b32_e32 v246, v247
	s_nop 1
	v_add_f32_e32 v246, v246, v247
	v_mov_b32_e32 v247, v246
	s_nop 1
	v_permlane32_swap_b32_e32 v246, v247
	v_add_u32_e32 v248, s8, v223
	s_nop 0
	v_add_f32_e32 v246, v246, v247
	s_mov_b64 exec, s[44:45]
	ds_write_b32 v248, v246 offset:512
	s_mov_b64 exec, -1
	v_pk_mul_f32 v[102:103], v[180:181], v[102:103]
	v_pk_mul_f32 v[104:105], v[182:183], v[104:105]
	v_pk_mul_f32 v[98:99], v[184:185], v[98:99]
	v_pk_mul_f32 v[100:101], v[186:187], v[100:101]
	v_pk_mul_f32 v[92:93], v[188:189], v[92:93]
	v_pk_mul_f32 v[94:95], v[190:191], v[94:95]
	v_pk_mul_f32 v[88:89], v[192:193], v[88:89]
	v_pk_mul_f32 v[90:91], v[194:195], v[90:91]
	v_cvt_pk_bf16_f32 v246, v102, v103
	v_cvt_pk_bf16_f32 v247, v104, v105
	v_cvt_pk_bf16_f32 v248, v98, v99
	v_cvt_pk_bf16_f32 v249, v100, v101
	v_cvt_pk_bf16_f32 v250, v92, v93
	v_cvt_pk_bf16_f32 v251, v94, v95
	v_cvt_pk_bf16_f32 v208, v88, v89
	v_cvt_pk_bf16_f32 v209, v90, v91
	s_add_u32 s2, s2, 0x8000
	s_addc_u32 s3, s3, 0
	s_add_u32 s18, s18, 0x8000
	s_addc_u32 s19, s19, 0
	s_add_u32 s78, s78, 0x8000
	s_addc_u32 s79, s79, 0
	s_add_u32 s22, s22, 0x8000
	s_addc_u32 s23, s23, 0
	s_mov_b64 vcc, s[6:7]
	v_cndmask_b32_dpp v102, v4, v0, vcc row_ror:8 row_mask:0xf bank_mask:0xf
	v_cndmask_b32_dpp v103, v5, v1, vcc row_ror:8 row_mask:0xf bank_mask:0xf
	v_cndmask_b32_dpp v104, v6, v2, vcc row_ror:8 row_mask:0xf bank_mask:0xf
	v_cndmask_b32_dpp v105, v7, v3, vcc row_ror:8 row_mask:0xf bank_mask:0xf
	v_cndmask_b32_dpp v92, v250, v246, vcc row_ror:8 row_mask:0xf bank_mask:0xf
	v_cndmask_b32_dpp v93, v251, v247, vcc row_ror:8 row_mask:0xf bank_mask:0xf
	v_cndmask_b32_dpp v94, v208, v248, vcc row_ror:8 row_mask:0xf bank_mask:0xf
	v_cndmask_b32_dpp v95, v209, v249, vcc row_ror:8 row_mask:0xf bank_mask:0xf
	s_not_b64 vcc, s[6:7]
	v_cndmask_b32_dpp v98, v0, v4, vcc row_ror:8 row_mask:0xf bank_mask:0xf
	v_cndmask_b32_dpp v99, v1, v5, vcc row_ror:8 row_mask:0xf bank_mask:0xf
	v_cndmask_b32_dpp v100, v2, v6, vcc row_ror:8 row_mask:0xf bank_mask:0xf
	v_cndmask_b32_dpp v101, v3, v7, vcc row_ror:8 row_mask:0xf bank_mask:0xf
	v_cndmask_b32_dpp v88, v246, v250, vcc row_ror:8 row_mask:0xf bank_mask:0xf
	v_cndmask_b32_dpp v89, v247, v251, vcc row_ror:8 row_mask:0xf bank_mask:0xf
	v_cndmask_b32_dpp v90, v248, v208, vcc row_ror:8 row_mask:0xf bank_mask:0xf
	v_cndmask_b32_dpp v91, v249, v209, vcc row_ror:8 row_mask:0xf bank_mask:0xf
	global_store_dwordx4 v171, v[102:105], s[2:3] nt
	global_store_dwordx4 v171, v[98:101], s[18:19] nt
	global_store_dwordx4 v171, v[92:95], s[78:79]
	global_store_dwordx4 v171, v[88:91], s[22:23]
	s_waitcnt vmcnt(6)
	v_pk_fma_f32 v[84:85], v[84:85], v[142:143], v[196:197]
	v_pk_fma_f32 v[86:87], v[86:87], v[144:145], v[198:199]
	v_pk_fma_f32 v[80:81], v[80:81], v[150:151], v[200:201]
	v_pk_fma_f32 v[82:83], v[82:83], v[152:153], v[202:203]
	v_pk_fma_f32 v[76:77], v[76:77], v[138:139], v[204:205]
	v_pk_fma_f32 v[78:79], v[78:79], v[140:141], v[206:207]
	v_pk_fma_f32 v[72:73], v[72:73], v[146:147], v[234:235]
	v_pk_fma_f32 v[74:75], v[74:75], v[148:149], v[236:237]
	global_load_dwordx4 v[196:199], v96, s[14:15] offset:128
	global_load_dwordx4 v[200:203], v96, s[14:15] offset:144
	s_add_u32 s14, s14, 0x10000
	s_addc_u32 s15, s15, 0
	global_load_dwordx4 v[204:207], v96, s[14:15]
	global_load_dwordx4 v[234:237], v96, s[14:15] offset:16
	v_cvt_pk_bf16_f32 v0, v84, v85
	v_cvt_pk_bf16_f32 v1, v86, v87
	v_cvt_pk_bf16_f32 v2, v80, v81
	v_cvt_pk_bf16_f32 v3, v82, v83
	v_cvt_pk_bf16_f32 v4, v76, v77
	v_cvt_pk_bf16_f32 v5, v78, v79
	v_cvt_pk_bf16_f32 v6, v72, v73
	v_cvt_pk_bf16_f32 v7, v74, v75
	v_mul_f32_e32 v246, v85, v85
	v_mul_f32_e32 v248, v87, v87
	v_fmac_f32_e32 v246, v84, v84
	v_fmac_f32_e32 v248, v86, v86
	v_add_f32_e32 v246, v246, v248
	v_mul_f32_e32 v248, v81, v81
	v_fmac_f32_e32 v248, v80, v80
	v_add_f32_e32 v246, v246, v248
	v_mul_f32_e32 v248, v83, v83
	v_fmac_f32_e32 v248, v82, v82
	v_add_f32_e32 v246, v248, v246
	v_mul_f32_e32 v247, v77, v77
	v_mul_f32_e32 v248, v79, v79
	v_fmac_f32_e32 v247, v76, v76
	v_fmac_f32_e32 v248, v78, v78
	v_add_f32_e32 v247, v247, v248
	v_mul_f32_e32 v248, v73, v73
	v_fmac_f32_e32 v248, v72, v72
	v_add_f32_e32 v247, v247, v248
	v_mul_f32_e32 v248, v75, v75
	v_fmac_f32_e32 v248, v74, v74
	v_add_f32_e32 v247, v248, v247
	v_add_f32_e32 v246, v246, v247
	v_mov_b32_e32 v247, v246
	s_nop 1
	v_permlane16_swap_b32_e32 v246, v247
	s_nop 1
	v_add_f32_e32 v246, v246, v247
	v_mov_b32_e32 v247, v246
	s_nop 1
	v_permlane32_swap_b32_e32 v246, v247
	v_add_u32_e32 v248, s8, v223
	s_nop 0
	v_add_f32_e32 v246, v246, v247
	s_mov_b64 exec, s[44:45]
	ds_write_b32 v248, v246 offset:768
	s_mov_b64 exec, -1
	v_pk_mul_f32 v[84:85], v[180:181], v[84:85]
	v_pk_mul_f32 v[86:87], v[182:183], v[86:87]
	v_pk_mul_f32 v[80:81], v[184:185], v[80:81]
	v_pk_mul_f32 v[82:83], v[186:187], v[82:83]
	v_pk_mul_f32 v[76:77], v[188:189], v[76:77]
	v_pk_mul_f32 v[78:79], v[190:191], v[78:79]
	v_pk_mul_f32 v[72:73], v[192:193], v[72:73]
	v_pk_mul_f32 v[74:75], v[194:195], v[74:75]
	v_cvt_pk_bf16_f32 v246, v84, v85
	v_cvt_pk_bf16_f32 v247, v86, v87
	v_cvt_pk_bf16_f32 v248, v80, v81
	v_cvt_pk_bf16_f32 v249, v82, v83
	v_cvt_pk_bf16_f32 v250, v76, v77
	v_cvt_pk_bf16_f32 v251, v78, v79
	v_cvt_pk_bf16_f32 v208, v72, v73
	v_cvt_pk_bf16_f32 v209, v74, v75
	s_add_u32 s2, s2, 0x8000
	s_addc_u32 s3, s3, 0
	s_add_u32 s18, s18, 0x8000
	s_addc_u32 s19, s19, 0
	s_add_u32 s78, s78, 0x8000
	s_addc_u32 s79, s79, 0
	s_add_u32 s22, s22, 0x8000
	s_addc_u32 s23, s23, 0
	s_mov_b64 vcc, s[6:7]
	v_cndmask_b32_dpp v84, v4, v0, vcc row_ror:8 row_mask:0xf bank_mask:0xf
	v_cndmask_b32_dpp v85, v5, v1, vcc row_ror:8 row_mask:0xf bank_mask:0xf
	v_cndmask_b32_dpp v86, v6, v2, vcc row_ror:8 row_mask:0xf bank_mask:0xf
	v_cndmask_b32_dpp v87, v7, v3, vcc row_ror:8 row_mask:0xf bank_mask:0xf
	v_cndmask_b32_dpp v76, v250, v246, vcc row_ror:8 row_mask:0xf bank_mask:0xf
	v_cndmask_b32_dpp v77, v251, v247, vcc row_ror:8 row_mask:0xf bank_mask:0xf
	v_cndmask_b32_dpp v78, v208, v248, vcc row_ror:8 row_mask:0xf bank_mask:0xf
	v_cndmask_b32_dpp v79, v209, v249, vcc row_ror:8 row_mask:0xf bank_mask:0xf
	s_not_b64 vcc, s[6:7]
	v_cndmask_b32_dpp v80, v0, v4, vcc row_ror:8 row_mask:0xf bank_mask:0xf
	v_cndmask_b32_dpp v81, v1, v5, vcc row_ror:8 row_mask:0xf bank_mask:0xf
	v_cndmask_b32_dpp v82, v2, v6, vcc row_ror:8 row_mask:0xf bank_mask:0xf
	v_cndmask_b32_dpp v83, v3, v7, vcc row_ror:8 row_mask:0xf bank_mask:0xf
	v_cndmask_b32_dpp v72, v246, v250, vcc row_ror:8 row_mask:0xf bank_mask:0xf
	v_cndmask_b32_dpp v73, v247, v251, vcc row_ror:8 row_mask:0xf bank_mask:0xf
	v_cndmask_b32_dpp v74, v248, v208, vcc row_ror:8 row_mask:0xf bank_mask:0xf
	v_cndmask_b32_dpp v75, v249, v209, vcc row_ror:8 row_mask:0xf bank_mask:0xf
	global_store_dwordx4 v171, v[84:87], s[2:3] nt
	global_store_dwordx4 v171, v[80:83], s[18:19] nt
	global_store_dwordx4 v171, v[76:79], s[78:79]
	global_store_dwordx4 v171, v[72:75], s[22:23]
	s_waitcnt vmcnt(6)
	v_pk_fma_f32 v[68:69], v[68:69], v[142:143], v[238:239]
	v_pk_fma_f32 v[70:71], v[70:71], v[144:145], v[240:241]
	v_pk_fma_f32 v[64:65], v[64:65], v[150:151], v[242:243]
	v_pk_fma_f32 v[66:67], v[66:67], v[152:153], v[244:245]
	v_pk_fma_f32 v[60:61], v[60:61], v[138:139], v[196:197]
	v_pk_fma_f32 v[62:63], v[62:63], v[140:141], v[198:199]
	v_pk_fma_f32 v[56:57], v[56:57], v[146:147], v[200:201]
	v_pk_fma_f32 v[58:59], v[58:59], v[148:149], v[202:203]
	global_load_dwordx4 v[238:241], v96, s[14:15] offset:128
	global_load_dwordx4 v[242:245], v96, s[14:15] offset:144
	s_add_u32 s14, s14, 0x10000
	s_addc_u32 s15, s15, 0
	global_load_dwordx4 v[196:199], v96, s[14:15]
	global_load_dwordx4 v[200:203], v96, s[14:15] offset:16
	v_cvt_pk_bf16_f32 v0, v68, v69
	v_cvt_pk_bf16_f32 v1, v70, v71
	v_cvt_pk_bf16_f32 v2, v64, v65
	v_cvt_pk_bf16_f32 v3, v66, v67
	v_cvt_pk_bf16_f32 v4, v60, v61
	v_cvt_pk_bf16_f32 v5, v62, v63
	v_cvt_pk_bf16_f32 v6, v56, v57
	v_cvt_pk_bf16_f32 v7, v58, v59
	v_mul_f32_e32 v246, v69, v69
	v_mul_f32_e32 v248, v71, v71
	v_fmac_f32_e32 v246, v68, v68
	v_fmac_f32_e32 v248, v70, v70
	v_add_f32_e32 v246, v246, v248
	v_mul_f32_e32 v248, v65, v65
	v_fmac_f32_e32 v248, v64, v64
	v_add_f32_e32 v246, v246, v248
	v_mul_f32_e32 v248, v67, v67
	v_fmac_f32_e32 v248, v66, v66
	v_add_f32_e32 v246, v248, v246
	v_mul_f32_e32 v247, v61, v61
	v_mul_f32_e32 v248, v63, v63
	v_fmac_f32_e32 v247, v60, v60
	v_fmac_f32_e32 v248, v62, v62
	v_add_f32_e32 v247, v247, v248
	v_mul_f32_e32 v248, v57, v57
	v_fmac_f32_e32 v248, v56, v56
	v_add_f32_e32 v247, v247, v248
	v_mul_f32_e32 v248, v59, v59
	v_fmac_f32_e32 v248, v58, v58
	v_add_f32_e32 v247, v248, v247
	v_add_f32_e32 v246, v246, v247
	v_mov_b32_e32 v247, v246
	s_nop 1
	v_permlane16_swap_b32_e32 v246, v247
	s_nop 1
	v_add_f32_e32 v246, v246, v247
	v_mov_b32_e32 v247, v246
	s_nop 1
	v_permlane32_swap_b32_e32 v246, v247
	v_add_u32_e32 v248, s8, v223
	s_nop 0
	v_add_f32_e32 v246, v246, v247
	s_mov_b64 exec, s[44:45]
	ds_write_b32 v248, v246 offset:2048
	s_mov_b64 exec, -1
	v_pk_mul_f32 v[68:69], v[180:181], v[68:69]
	v_pk_mul_f32 v[70:71], v[182:183], v[70:71]
	v_pk_mul_f32 v[64:65], v[184:185], v[64:65]
	v_pk_mul_f32 v[66:67], v[186:187], v[66:67]
	v_pk_mul_f32 v[60:61], v[188:189], v[60:61]
	v_pk_mul_f32 v[62:63], v[190:191], v[62:63]
	v_pk_mul_f32 v[56:57], v[192:193], v[56:57]
	v_pk_mul_f32 v[58:59], v[194:195], v[58:59]
	v_cvt_pk_bf16_f32 v246, v68, v69
	v_cvt_pk_bf16_f32 v247, v70, v71
	v_cvt_pk_bf16_f32 v248, v64, v65
	v_cvt_pk_bf16_f32 v249, v66, v67
	v_cvt_pk_bf16_f32 v250, v60, v61
	v_cvt_pk_bf16_f32 v251, v62, v63
	v_cvt_pk_bf16_f32 v208, v56, v57
	v_cvt_pk_bf16_f32 v209, v58, v59
	s_add_u32 s2, s2, 0x28000
	s_addc_u32 s3, s3, 0
	s_add_u32 s18, s18, 0x28000
	s_addc_u32 s19, s19, 0
	s_add_u32 s78, s78, 0x28000
	s_addc_u32 s79, s79, 0
	s_add_u32 s22, s22, 0x28000
	s_addc_u32 s23, s23, 0
	s_mov_b64 vcc, s[6:7]
	v_cndmask_b32_dpp v68, v4, v0, vcc row_ror:8 row_mask:0xf bank_mask:0xf
	v_cndmask_b32_dpp v69, v5, v1, vcc row_ror:8 row_mask:0xf bank_mask:0xf
	v_cndmask_b32_dpp v70, v6, v2, vcc row_ror:8 row_mask:0xf bank_mask:0xf
	v_cndmask_b32_dpp v71, v7, v3, vcc row_ror:8 row_mask:0xf bank_mask:0xf
	v_cndmask_b32_dpp v60, v250, v246, vcc row_ror:8 row_mask:0xf bank_mask:0xf
	v_cndmask_b32_dpp v61, v251, v247, vcc row_ror:8 row_mask:0xf bank_mask:0xf
	v_cndmask_b32_dpp v62, v208, v248, vcc row_ror:8 row_mask:0xf bank_mask:0xf
	v_cndmask_b32_dpp v63, v209, v249, vcc row_ror:8 row_mask:0xf bank_mask:0xf
	s_not_b64 vcc, s[6:7]
	v_cndmask_b32_dpp v64, v0, v4, vcc row_ror:8 row_mask:0xf bank_mask:0xf
	v_cndmask_b32_dpp v65, v1, v5, vcc row_ror:8 row_mask:0xf bank_mask:0xf
	v_cndmask_b32_dpp v66, v2, v6, vcc row_ror:8 row_mask:0xf bank_mask:0xf
	v_cndmask_b32_dpp v67, v3, v7, vcc row_ror:8 row_mask:0xf bank_mask:0xf
	v_cndmask_b32_dpp v56, v246, v250, vcc row_ror:8 row_mask:0xf bank_mask:0xf
	v_cndmask_b32_dpp v57, v247, v251, vcc row_ror:8 row_mask:0xf bank_mask:0xf
	v_cndmask_b32_dpp v58, v248, v208, vcc row_ror:8 row_mask:0xf bank_mask:0xf
	v_cndmask_b32_dpp v59, v249, v209, vcc row_ror:8 row_mask:0xf bank_mask:0xf
	global_store_dwordx4 v171, v[68:71], s[2:3] nt
	global_store_dwordx4 v171, v[64:67], s[18:19] nt
	global_store_dwordx4 v171, v[60:63], s[78:79]
	global_store_dwordx4 v171, v[56:59], s[22:23]
	s_waitcnt vmcnt(6)
	v_pk_fma_f32 v[52:53], v[52:53], v[142:143], v[204:205]
	v_pk_fma_f32 v[54:55], v[54:55], v[144:145], v[206:207]
	v_pk_fma_f32 v[48:49], v[48:49], v[150:151], v[234:235]
	v_pk_fma_f32 v[50:51], v[50:51], v[152:153], v[236:237]
	v_pk_fma_f32 v[44:45], v[44:45], v[138:139], v[238:239]
	v_pk_fma_f32 v[46:47], v[46:47], v[140:141], v[240:241]
	v_pk_fma_f32 v[40:41], v[40:41], v[146:147], v[242:243]
	v_pk_fma_f32 v[42:43], v[42:43], v[148:149], v[244:245]
	global_load_dwordx4 v[204:207], v96, s[14:15] offset:128
	global_load_dwordx4 v[234:237], v96, s[14:15] offset:144
	s_add_u32 s14, s14, 0x10000
	s_addc_u32 s15, s15, 0
	global_load_dwordx4 v[238:241], v96, s[14:15]
	global_load_dwordx4 v[242:245], v96, s[14:15] offset:16
	v_cvt_pk_bf16_f32 v0, v52, v53
	v_cvt_pk_bf16_f32 v1, v54, v55
	v_cvt_pk_bf16_f32 v2, v48, v49
	v_cvt_pk_bf16_f32 v3, v50, v51
	v_cvt_pk_bf16_f32 v4, v44, v45
	v_cvt_pk_bf16_f32 v5, v46, v47
	v_cvt_pk_bf16_f32 v6, v40, v41
	v_cvt_pk_bf16_f32 v7, v42, v43
	v_mul_f32_e32 v246, v53, v53
	v_mul_f32_e32 v248, v55, v55
	v_fmac_f32_e32 v246, v52, v52
	v_fmac_f32_e32 v248, v54, v54
	v_add_f32_e32 v246, v246, v248
	v_mul_f32_e32 v248, v49, v49
	v_fmac_f32_e32 v248, v48, v48
	v_add_f32_e32 v246, v246, v248
	v_mul_f32_e32 v248, v51, v51
	v_fmac_f32_e32 v248, v50, v50
	v_add_f32_e32 v246, v248, v246
	v_mul_f32_e32 v247, v45, v45
	v_mul_f32_e32 v248, v47, v47
	v_fmac_f32_e32 v247, v44, v44
	v_fmac_f32_e32 v248, v46, v46
	v_add_f32_e32 v247, v247, v248
	v_mul_f32_e32 v248, v41, v41
	v_fmac_f32_e32 v248, v40, v40
	v_add_f32_e32 v247, v247, v248
	v_mul_f32_e32 v248, v43, v43
	v_fmac_f32_e32 v248, v42, v42
	v_add_f32_e32 v247, v248, v247
	v_add_f32_e32 v246, v246, v247
	v_mov_b32_e32 v247, v246
	s_nop 1
	v_permlane16_swap_b32_e32 v246, v247
	s_nop 1
	v_add_f32_e32 v246, v246, v247
	v_mov_b32_e32 v247, v246
	s_nop 1
	v_permlane32_swap_b32_e32 v246, v247
	v_add_u32_e32 v248, s8, v223
	s_nop 0
	v_add_f32_e32 v246, v246, v247
	s_mov_b64 exec, s[44:45]
	ds_write_b32 v248, v246 offset:2304
	s_mov_b64 exec, -1
	v_pk_mul_f32 v[52:53], v[180:181], v[52:53]
	v_pk_mul_f32 v[54:55], v[182:183], v[54:55]
	v_pk_mul_f32 v[48:49], v[184:185], v[48:49]
	v_pk_mul_f32 v[50:51], v[186:187], v[50:51]
	v_pk_mul_f32 v[44:45], v[188:189], v[44:45]
	v_pk_mul_f32 v[46:47], v[190:191], v[46:47]
	v_pk_mul_f32 v[40:41], v[192:193], v[40:41]
	v_pk_mul_f32 v[42:43], v[194:195], v[42:43]
	v_cvt_pk_bf16_f32 v246, v52, v53
	v_cvt_pk_bf16_f32 v247, v54, v55
	v_cvt_pk_bf16_f32 v248, v48, v49
	v_cvt_pk_bf16_f32 v249, v50, v51
	v_cvt_pk_bf16_f32 v250, v44, v45
	v_cvt_pk_bf16_f32 v251, v46, v47
	v_cvt_pk_bf16_f32 v208, v40, v41
	v_cvt_pk_bf16_f32 v209, v42, v43
	s_add_u32 s2, s2, 0x8000
	s_addc_u32 s3, s3, 0
	s_add_u32 s18, s18, 0x8000
	s_addc_u32 s19, s19, 0
	s_add_u32 s78, s78, 0x8000
	s_addc_u32 s79, s79, 0
	s_add_u32 s22, s22, 0x8000
	s_addc_u32 s23, s23, 0
	s_mov_b64 vcc, s[6:7]
	v_cndmask_b32_dpp v52, v4, v0, vcc row_ror:8 row_mask:0xf bank_mask:0xf
	v_cndmask_b32_dpp v53, v5, v1, vcc row_ror:8 row_mask:0xf bank_mask:0xf
	v_cndmask_b32_dpp v54, v6, v2, vcc row_ror:8 row_mask:0xf bank_mask:0xf
	v_cndmask_b32_dpp v55, v7, v3, vcc row_ror:8 row_mask:0xf bank_mask:0xf
	v_cndmask_b32_dpp v44, v250, v246, vcc row_ror:8 row_mask:0xf bank_mask:0xf
	v_cndmask_b32_dpp v45, v251, v247, vcc row_ror:8 row_mask:0xf bank_mask:0xf
	v_cndmask_b32_dpp v46, v208, v248, vcc row_ror:8 row_mask:0xf bank_mask:0xf
	v_cndmask_b32_dpp v47, v209, v249, vcc row_ror:8 row_mask:0xf bank_mask:0xf
	s_not_b64 vcc, s[6:7]
	v_cndmask_b32_dpp v48, v0, v4, vcc row_ror:8 row_mask:0xf bank_mask:0xf
	v_cndmask_b32_dpp v49, v1, v5, vcc row_ror:8 row_mask:0xf bank_mask:0xf
	v_cndmask_b32_dpp v50, v2, v6, vcc row_ror:8 row_mask:0xf bank_mask:0xf
	v_cndmask_b32_dpp v51, v3, v7, vcc row_ror:8 row_mask:0xf bank_mask:0xf
	v_cndmask_b32_dpp v40, v246, v250, vcc row_ror:8 row_mask:0xf bank_mask:0xf
	v_cndmask_b32_dpp v41, v247, v251, vcc row_ror:8 row_mask:0xf bank_mask:0xf
	v_cndmask_b32_dpp v42, v248, v208, vcc row_ror:8 row_mask:0xf bank_mask:0xf
	v_cndmask_b32_dpp v43, v249, v209, vcc row_ror:8 row_mask:0xf bank_mask:0xf
	global_store_dwordx4 v171, v[52:55], s[2:3] nt
	global_store_dwordx4 v171, v[48:51], s[18:19] nt
	global_store_dwordx4 v171, v[44:47], s[78:79]
	global_store_dwordx4 v171, v[40:43], s[22:23]
	s_waitcnt vmcnt(6)
	v_pk_fma_f32 v[36:37], v[36:37], v[142:143], v[196:197]
	v_pk_fma_f32 v[38:39], v[38:39], v[144:145], v[198:199]
	v_pk_fma_f32 v[32:33], v[32:33], v[150:151], v[200:201]
	v_pk_fma_f32 v[34:35], v[34:35], v[152:153], v[202:203]
	v_pk_fma_f32 v[28:29], v[28:29], v[138:139], v[204:205]
	v_pk_fma_f32 v[30:31], v[30:31], v[140:141], v[206:207]
	v_pk_fma_f32 v[24:25], v[24:25], v[146:147], v[234:235]
	v_pk_fma_f32 v[26:27], v[26:27], v[148:149], v[236:237]
	global_load_dwordx4 v[196:199], v96, s[14:15] offset:128
	global_load_dwordx4 v[200:203], v96, s[14:15] offset:144
	v_cvt_pk_bf16_f32 v0, v36, v37
	v_cvt_pk_bf16_f32 v1, v38, v39
	v_cvt_pk_bf16_f32 v2, v32, v33
	v_cvt_pk_bf16_f32 v3, v34, v35
	v_cvt_pk_bf16_f32 v4, v28, v29
	v_cvt_pk_bf16_f32 v5, v30, v31
	v_cvt_pk_bf16_f32 v6, v24, v25
	v_cvt_pk_bf16_f32 v7, v26, v27
	v_mul_f32_e32 v246, v37, v37
	v_mul_f32_e32 v248, v39, v39
	v_fmac_f32_e32 v246, v36, v36
	v_fmac_f32_e32 v248, v38, v38
	v_add_f32_e32 v246, v246, v248
	v_mul_f32_e32 v248, v33, v33
	v_fmac_f32_e32 v248, v32, v32
	v_add_f32_e32 v246, v246, v248
	v_mul_f32_e32 v248, v35, v35
	v_fmac_f32_e32 v248, v34, v34
	v_add_f32_e32 v246, v248, v246
	v_mul_f32_e32 v247, v29, v29
	v_mul_f32_e32 v248, v31, v31
	v_fmac_f32_e32 v247, v28, v28
	v_fmac_f32_e32 v248, v30, v30
	v_add_f32_e32 v247, v247, v248
	v_mul_f32_e32 v248, v25, v25
	v_fmac_f32_e32 v248, v24, v24
	v_add_f32_e32 v247, v247, v248
	v_mul_f32_e32 v248, v27, v27
	v_fmac_f32_e32 v248, v26, v26
	v_add_f32_e32 v247, v248, v247
	v_add_f32_e32 v246, v246, v247
	v_mov_b32_e32 v247, v246
	s_nop 1
	v_permlane16_swap_b32_e32 v246, v247
	s_nop 1
	v_add_f32_e32 v246, v246, v247
	v_mov_b32_e32 v247, v246
	s_nop 1
	v_permlane32_swap_b32_e32 v246, v247
	v_add_u32_e32 v248, s8, v223
	s_nop 0
	v_add_f32_e32 v246, v246, v247
	s_mov_b64 exec, s[44:45]
	ds_write_b32 v248, v246 offset:2560
	s_mov_b64 exec, -1
	v_pk_mul_f32 v[36:37], v[180:181], v[36:37]
	v_pk_mul_f32 v[38:39], v[182:183], v[38:39]
	v_pk_mul_f32 v[32:33], v[184:185], v[32:33]
	v_pk_mul_f32 v[34:35], v[186:187], v[34:35]
	v_pk_mul_f32 v[28:29], v[188:189], v[28:29]
	v_pk_mul_f32 v[30:31], v[190:191], v[30:31]
	v_pk_mul_f32 v[24:25], v[192:193], v[24:25]
	v_pk_mul_f32 v[26:27], v[194:195], v[26:27]
	v_cvt_pk_bf16_f32 v246, v36, v37
	v_cvt_pk_bf16_f32 v247, v38, v39
	v_cvt_pk_bf16_f32 v248, v32, v33
	v_cvt_pk_bf16_f32 v249, v34, v35
	v_cvt_pk_bf16_f32 v250, v28, v29
	v_cvt_pk_bf16_f32 v251, v30, v31
	v_cvt_pk_bf16_f32 v208, v24, v25
	v_cvt_pk_bf16_f32 v209, v26, v27
	s_add_u32 s2, s2, 0x8000
	s_addc_u32 s3, s3, 0
	s_add_u32 s18, s18, 0x8000
	s_addc_u32 s19, s19, 0
	s_add_u32 s78, s78, 0x8000
	s_addc_u32 s79, s79, 0
	s_add_u32 s22, s22, 0x8000
	s_addc_u32 s23, s23, 0
	s_mov_b64 vcc, s[6:7]
	v_cndmask_b32_dpp v36, v4, v0, vcc row_ror:8 row_mask:0xf bank_mask:0xf
	v_cndmask_b32_dpp v37, v5, v1, vcc row_ror:8 row_mask:0xf bank_mask:0xf
	v_cndmask_b32_dpp v38, v6, v2, vcc row_ror:8 row_mask:0xf bank_mask:0xf
	v_cndmask_b32_dpp v39, v7, v3, vcc row_ror:8 row_mask:0xf bank_mask:0xf
	v_cndmask_b32_dpp v28, v250, v246, vcc row_ror:8 row_mask:0xf bank_mask:0xf
	v_cndmask_b32_dpp v29, v251, v247, vcc row_ror:8 row_mask:0xf bank_mask:0xf
	v_cndmask_b32_dpp v30, v208, v248, vcc row_ror:8 row_mask:0xf bank_mask:0xf
	v_cndmask_b32_dpp v31, v209, v249, vcc row_ror:8 row_mask:0xf bank_mask:0xf
	s_not_b64 vcc, s[6:7]
	v_cndmask_b32_dpp v32, v0, v4, vcc row_ror:8 row_mask:0xf bank_mask:0xf
	v_cndmask_b32_dpp v33, v1, v5, vcc row_ror:8 row_mask:0xf bank_mask:0xf
	v_cndmask_b32_dpp v34, v2, v6, vcc row_ror:8 row_mask:0xf bank_mask:0xf
	v_cndmask_b32_dpp v35, v3, v7, vcc row_ror:8 row_mask:0xf bank_mask:0xf
	v_cndmask_b32_dpp v24, v246, v250, vcc row_ror:8 row_mask:0xf bank_mask:0xf
	v_cndmask_b32_dpp v25, v247, v251, vcc row_ror:8 row_mask:0xf bank_mask:0xf
	v_cndmask_b32_dpp v26, v248, v208, vcc row_ror:8 row_mask:0xf bank_mask:0xf
	v_cndmask_b32_dpp v27, v249, v209, vcc row_ror:8 row_mask:0xf bank_mask:0xf
	global_store_dwordx4 v171, v[36:39], s[2:3] nt
	global_store_dwordx4 v171, v[32:35], s[18:19] nt
	global_store_dwordx4 v171, v[28:31], s[78:79]
	global_store_dwordx4 v171, v[24:27], s[22:23]
	s_waitcnt vmcnt(4)
	v_pk_fma_f32 v[20:21], v[20:21], v[142:143], v[238:239]
	v_pk_fma_f32 v[22:23], v[22:23], v[144:145], v[240:241]
	v_pk_fma_f32 v[16:17], v[16:17], v[150:151], v[242:243]
	v_pk_fma_f32 v[18:19], v[18:19], v[152:153], v[244:245]
	v_pk_fma_f32 v[12:13], v[12:13], v[138:139], v[196:197]
	v_pk_fma_f32 v[14:15], v[14:15], v[140:141], v[198:199]
	v_pk_fma_f32 v[8:9], v[8:9], v[146:147], v[200:201]
	v_pk_fma_f32 v[10:11], v[10:11], v[148:149], v[202:203]
	v_cvt_pk_bf16_f32 v0, v20, v21
	v_cvt_pk_bf16_f32 v1, v22, v23
	v_cvt_pk_bf16_f32 v2, v16, v17
	v_cvt_pk_bf16_f32 v3, v18, v19
	v_cvt_pk_bf16_f32 v4, v12, v13
	v_cvt_pk_bf16_f32 v5, v14, v15
	v_cvt_pk_bf16_f32 v6, v8, v9
	v_cvt_pk_bf16_f32 v7, v10, v11
	v_mul_f32_e32 v246, v21, v21
	v_mul_f32_e32 v248, v23, v23
	v_fmac_f32_e32 v246, v20, v20
	v_fmac_f32_e32 v248, v22, v22
	v_add_f32_e32 v246, v246, v248
	v_mul_f32_e32 v248, v17, v17
	v_fmac_f32_e32 v248, v16, v16
	v_add_f32_e32 v246, v246, v248
	v_mul_f32_e32 v248, v19, v19
	v_fmac_f32_e32 v248, v18, v18
	v_add_f32_e32 v246, v248, v246
	v_mul_f32_e32 v247, v13, v13
	v_mul_f32_e32 v248, v15, v15
	v_fmac_f32_e32 v247, v12, v12
	v_fmac_f32_e32 v248, v14, v14
	v_add_f32_e32 v247, v247, v248
	v_mul_f32_e32 v248, v9, v9
	v_fmac_f32_e32 v248, v8, v8
	v_add_f32_e32 v247, v247, v248
	v_mul_f32_e32 v248, v11, v11
	v_fmac_f32_e32 v248, v10, v10
	v_add_f32_e32 v247, v248, v247
	v_add_f32_e32 v246, v246, v247
	v_mov_b32_e32 v247, v246
	s_nop 1
	v_permlane16_swap_b32_e32 v246, v247
	s_nop 1
	v_add_f32_e32 v246, v246, v247
	v_mov_b32_e32 v247, v246
	s_nop 1
	v_permlane32_swap_b32_e32 v246, v247
	v_add_u32_e32 v248, s8, v223
	s_nop 0
	v_add_f32_e32 v246, v246, v247
	s_mov_b64 exec, s[44:45]
	ds_write_b32 v248, v246 offset:2816
	s_mov_b64 exec, -1
	v_pk_mul_f32 v[20:21], v[180:181], v[20:21]
	v_pk_mul_f32 v[22:23], v[182:183], v[22:23]
	v_pk_mul_f32 v[16:17], v[184:185], v[16:17]
	v_pk_mul_f32 v[18:19], v[186:187], v[18:19]
	v_pk_mul_f32 v[12:13], v[188:189], v[12:13]
	v_pk_mul_f32 v[14:15], v[190:191], v[14:15]
	v_pk_mul_f32 v[8:9], v[192:193], v[8:9]
	v_pk_mul_f32 v[10:11], v[194:195], v[10:11]
	v_cvt_pk_bf16_f32 v246, v20, v21
	v_cvt_pk_bf16_f32 v247, v22, v23
	v_cvt_pk_bf16_f32 v248, v16, v17
	v_cvt_pk_bf16_f32 v249, v18, v19
	v_cvt_pk_bf16_f32 v250, v12, v13
	v_cvt_pk_bf16_f32 v251, v14, v15
	v_cvt_pk_bf16_f32 v208, v8, v9
	v_cvt_pk_bf16_f32 v209, v10, v11
	s_add_u32 s2, s2, 0x8000
	s_addc_u32 s3, s3, 0
	s_add_u32 s18, s18, 0x8000
	s_addc_u32 s19, s19, 0
	s_add_u32 s78, s78, 0x8000
	s_addc_u32 s79, s79, 0
	s_add_u32 s22, s22, 0x8000
	s_addc_u32 s23, s23, 0
	s_mov_b64 vcc, s[6:7]
	v_cndmask_b32_dpp v20, v4, v0, vcc row_ror:8 row_mask:0xf bank_mask:0xf
	v_cndmask_b32_dpp v21, v5, v1, vcc row_ror:8 row_mask:0xf bank_mask:0xf
	v_cndmask_b32_dpp v22, v6, v2, vcc row_ror:8 row_mask:0xf bank_mask:0xf
	v_cndmask_b32_dpp v23, v7, v3, vcc row_ror:8 row_mask:0xf bank_mask:0xf
	v_cndmask_b32_dpp v12, v250, v246, vcc row_ror:8 row_mask:0xf bank_mask:0xf
	v_cndmask_b32_dpp v13, v251, v247, vcc row_ror:8 row_mask:0xf bank_mask:0xf
	v_cndmask_b32_dpp v14, v208, v248, vcc row_ror:8 row_mask:0xf bank_mask:0xf
	v_cndmask_b32_dpp v15, v209, v249, vcc row_ror:8 row_mask:0xf bank_mask:0xf
	s_not_b64 vcc, s[6:7]
	v_cndmask_b32_dpp v16, v0, v4, vcc row_ror:8 row_mask:0xf bank_mask:0xf
	v_cndmask_b32_dpp v17, v1, v5, vcc row_ror:8 row_mask:0xf bank_mask:0xf
	v_cndmask_b32_dpp v18, v2, v6, vcc row_ror:8 row_mask:0xf bank_mask:0xf
	v_cndmask_b32_dpp v19, v3, v7, vcc row_ror:8 row_mask:0xf bank_mask:0xf
	v_cndmask_b32_dpp v8, v246, v250, vcc row_ror:8 row_mask:0xf bank_mask:0xf
	v_cndmask_b32_dpp v9, v247, v251, vcc row_ror:8 row_mask:0xf bank_mask:0xf
	v_cndmask_b32_dpp v10, v248, v208, vcc row_ror:8 row_mask:0xf bank_mask:0xf
	v_cndmask_b32_dpp v11, v249, v209, vcc row_ror:8 row_mask:0xf bank_mask:0xf
	global_store_dwordx4 v171, v[20:23], s[2:3] nt
	global_store_dwordx4 v171, v[16:19], s[18:19] nt
	global_store_dwordx4 v171, v[12:15], s[78:79]
	global_store_dwordx4 v171, v[8:11], s[22:23]
	s_mov_b32 s100, 1
	s_branch .LBB0_714
